# merge K loop: one lgkmcnt per k-step, one M0 write per DMA group (instruction offsets)
# baseline (speedup 1.0000x reference)
; DI void gemm_mid(const bf16_t* __restrict__ W, int ldw, const bf16_t* __restrict__ X, size_t ldx, int mclamp, int kts,
;                  int nkt, int m0, f32x16 (&acc)[2][2], bf16_t* lds) {
;     ...
;   __syncthreads();
;   GM_GLOAD(0)
;   GM_LSTORE(0)
;   __syncthreads();
; DI void phase_merge(const P& p, int layer, bf16_t* sm, const Geo& ge) {
;     ...
;   while (tw.next(mt_, nt_)) {
;     unsigned zp[2][2][8];
; #pragma unroll
;     for (int a_ = 0; a_ < 2; ++a_)
; #pragma unroll
;       for (int b_ = 0; b_ < 2; ++b_)
; #pragma unroll
;         for (int i = 0; i < 8; ++i) zp[a_][b_][i] = 0u;
;     for (int n3 = 0; n3 < 3; ++n3) {
;       const bf16_t* X = (const bf16_t*)(p.ws + (n3 == 0 ? O_AQ : (n3 == 1 ? O_BQ : O_CQ)));
;       f32x16 acc[2][2]; zero_acc(acc);
;       gemm_mid(W + ((size_t)n3 * 1024 + nt_ * 128) * 512, 512, X, 512, 1 << 30, 64, 8, mt_ * 256, acc, sm);
.LBB0_1090:
	s_and_b32 s0, s7, 0xffffff80
	s_ashr_i32 s1, s0, 31
	s_and_b32 s2, s6, 0x700
	s_add_i32 s8, s8, s10
	s_or_b32 s9, s2, s30
	s_lshl_b64 s[2:3], s[0:1], 10
	s_add_u32 s2, s4, s2
	s_addc_u32 s3, s5, s3
	v_and_b32_e32 v190, 63, v195
	v_lshrrev_b32_e32 v191, 6, v195
	v_and_b32_e32 v98, 31, v190
	v_lshrrev_b32_e32 v99, 5, v190
	v_bfe_u32 v100, v98, 1, 3
	v_lshlrev_b32_e32 v101, 7, v98
	v_xor_b32_e32 v102, v99, v100
	v_lshl_add_u32 v101, v102, 4, v101
	v_and_b32_e32 v102, 1, v191
	v_lshrrev_b32_e32 v103, 1, v191
	v_readfirstlane_b32 s50, v191
	v_lshl_add_u32 v168, v102, 13, v101
	v_lshl_add_u32 v172, v103, 13, v101
	v_add_u32_e32 v172, 0xc000, v172
	v_xor_b32_e32 v169, 0x20, v168
	v_xor_b32_e32 v173, 0x20, v172
	v_xor_b32_e32 v170, 0x40, v168
	v_xor_b32_e32 v174, 0x40, v172
	v_xor_b32_e32 v171, 0x60, v168
	v_xor_b32_e32 v175, 0x60, v172
	v_add_u32_e32 v176, 0x10000, v172
	v_add_u32_e32 v177, 0x10000, v173
	v_add_u32_e32 v178, 0x10000, v174
	v_add_u32_e32 v179, 0x10000, v175
	s_lshl_b32 s51, s50, 12
	s_lshl_b32 s50, s50, 11
	s_add_u32 s51, s51, 0xc000
	v_lshrrev_b32_e32 v104, 3, v190
	v_and_b32_e32 v105, 7, v190
	v_lshrrev_b32_e32 v192, 4, v190
	v_xor_b32_e32 v105, v105, v192
	v_lshlrev_b32_e32 v105, 4, v105
	v_lshl_add_u32 v192, v191, 4, v104
	v_lshl_add_u32 v180, v192, 10, v105
	v_xor_b32_e32 v181, 64, v180
	v_add_u32_e32 v181, 0x2000, v181
	v_lshl_add_u32 v192, v191, 5, v104
	v_lshl_add_u32 v182, v192, 10, v105
	v_xor_b32_e32 v183, 64, v182
	v_add_u32_e32 v183, 0x2000, v183
	v_add_u32_e32 v184, 0x4000, v182
	v_add_u32_e32 v185, 0x4000, v183
	v_subrev_u32_e32 v181, 0x400, v181
	v_subrev_u32_e32 v183, 0x400, v183
	v_subrev_u32_e32 v184, 0x800, v184
	v_subrev_u32_e32 v185, 0xc00, v185
	v_lshl_add_u32 v104, v103, 6, v98
	v_add_u32_e32 v104, s9, v104
	v_lshl_add_u32 v105, v102, 4, v99
	s_lshr_b32 s32, s0, 2
	v_add_u32_e32 v105, s32, v105
	v_lshlrev_b32_e32 v105, 17, v105
	v_lshl_add_u32 v186, v104, 3, v105
	v_lshrrev_b32_e32 v104, 3, v190
	v_lshl_add_u32 v104, v103, 6, v104
	v_add_u32_e32 v104, s9, v104
	s_movk_i32 s32, 0x880
	v_mul_lo_u32 v104, v104, s32
	v_and_b32_e32 v105, 7, v190
	v_lshlrev_b32_e32 v105, 4, v105
	v_lshl_add_u32 v105, v102, 7, v105
	s_lshl_b32 s32, s0, 1
	v_add3_u32 v187, v104, v105, s32
	s_movk_i32 s32, 0x2400
	v_mul_lo_u32 v104, v191, s32
	v_mul_u32_u24_e32 v105, 0x90, v98
	v_lshl_add_u32 v105, v99, 3, v105
	v_add_u32_e32 v188, v104, v105
	v_lshrrev_b32_e32 v105, 3, v190
	v_mul_u32_u24_e32 v105, 0x90, v105
	v_add_u32_e32 v105, v104, v105
	v_and_b32_e32 v104, 7, v190
	v_lshl_add_u32 v189, v104, 4, v105
	s_lshl_b32 s32, s9, 10
	s_add_u32 s48, s58, s32
	s_addc_u32 s49, s59, 0
	s_mov_b32 s46, s2
	s_mov_b32 s47, s3
	s_barrier
	s_mov_b32 m0, s50
	s_nop 0
	global_load_lds_dwordx4 v180, s[46:47]
	global_load_lds_dwordx4 v181, s[46:47] offset:1024
	s_add_u32 s46, s46, 0x80
	s_addc_u32 s47, s47, 0
	s_mov_b32 m0, s51
	s_nop 0
	global_load_lds_dwordx4 v182, s[48:49]
	global_load_lds_dwordx4 v183, s[48:49] offset:1024
	global_load_lds_dwordx4 v184, s[48:49] offset:2048
	global_load_lds_dwordx4 v185, s[48:49] offset:3072
	s_add_u32 s48, s48, 0x80
	s_addc_u32 s49, s49, 0
	s_add_u32 m0, s50, 0x4000
	s_nop 0
	global_load_lds_dwordx4 v180, s[46:47]
	global_load_lds_dwordx4 v181, s[46:47] offset:1024
	s_add_u32 s46, s46, 0x80
	s_addc_u32 s47, s47, 0
	s_add_u32 m0, s51, 0x8000
	s_nop 0
	global_load_lds_dwordx4 v182, s[48:49]
	global_load_lds_dwordx4 v183, s[48:49] offset:1024
	global_load_lds_dwordx4 v184, s[48:49] offset:2048
	global_load_lds_dwordx4 v185, s[48:49] offset:3072
	s_add_u32 s48, s48, 0x80
	s_addc_u32 s49, s49, 0
	s_add_u32 m0, s50, 0x8000
	s_nop 0
	global_load_lds_dwordx4 v180, s[46:47]
	global_load_lds_dwordx4 v181, s[46:47] offset:1024
	s_add_u32 s46, s46, 0x80
	s_addc_u32 s47, s47, 0
	s_add_u32 m0, s51, 0x10000
	s_nop 0
	global_load_lds_dwordx4 v182, s[48:49]
	global_load_lds_dwordx4 v183, s[48:49] offset:1024
	global_load_lds_dwordx4 v184, s[48:49] offset:2048
	global_load_lds_dwordx4 v185, s[48:49] offset:3072
	s_add_u32 s48, s48, 0x80
	s_addc_u32 s49, s49, 0
	v_add_u32_e32 v190, 0x0, v186
	global_load_dwordx2 v[196:197], v190, s[28:29] nt
	global_load_dwordx2 v[212:213], v190, s[28:29] offset:256 nt
	v_add_u32_e32 v191, 0x40000, v186
	global_load_dwordx2 v[198:199], v191, s[28:29] nt
	global_load_dwordx2 v[214:215], v191, s[28:29] offset:256 nt
	v_add_u32_e32 v190, 0x80000, v186
	global_load_dwordx2 v[200:201], v190, s[28:29] nt
	global_load_dwordx2 v[216:217], v190, s[28:29] offset:256 nt
	v_add_u32_e32 v191, 0xc0000, v186
	global_load_dwordx2 v[202:203], v191, s[28:29] nt
	global_load_dwordx2 v[218:219], v191, s[28:29] offset:256 nt
	v_add_u32_e32 v190, 0x100000, v186
	global_load_dwordx2 v[204:205], v190, s[28:29] nt
	global_load_dwordx2 v[236:237], v190, s[28:29] offset:256 nt
	v_add_u32_e32 v191, 0x140000, v186
	global_load_dwordx2 v[206:207], v191, s[28:29] nt
	global_load_dwordx2 v[238:239], v191, s[28:29] offset:256 nt
	v_add_u32_e32 v190, 0x180000, v186
	global_load_dwordx2 v[208:209], v190, s[28:29] nt
	global_load_dwordx2 v[240:241], v190, s[28:29] offset:256 nt
	v_add_u32_e32 v191, 0x1c0000, v186
	global_load_dwordx2 v[210:211], v191, s[28:29] nt
	global_load_dwordx2 v[242:243], v191, s[28:29] offset:256 nt
	s_waitcnt vmcnt(28)
	s_barrier
; #define MFMA32(a, b, c) __builtin_amdgcn_mfma_f32_32x32x16_bf16((a), (b), (c), 0, 0, 0)
; DI void gemm_mid(const bf16_t* __restrict__ W, int ldw, const bf16_t* __restrict__ X, size_t ldx, int mclamp, int kts,
;                  int nkt, int m0, f32x16 (&acc)[2][2], bf16_t* lds) {
;     ...
;   for (int kt = 0; kt < nkt; ++kt) {
;     const bool more = kt + 1 < nkt;
;     if (more) GM_GLOAD(kt + 1)
;     __builtin_amdgcn_sched_barrier(0);
;     {
;       const bf16_t* wb = lds + (kt & 1) * MID_E + (wn * 64 + lr) * LDT + lh * 8;
;       const bf16_t* xb = lds + (kt & 1) * MID_E + 128 * LDT + (wm * 64 + lr) * LDT + lh * 8;
; #pragma unroll
;       for (int ks = 0; ks < 4; ++ks) {
;         const bf16x8 a0 = *(const bf16x8*)(wb + ks * 16), a1 = *(const bf16x8*)(wb + 32 * LDT + ks * 16);
;         const bf16x8 b0 = *(const bf16x8*)(xb + ks * 16), b1 = *(const bf16x8*)(xb + 32 * LDT + ks * 16);
;         acc[0][0] = MFMA32(a0, b0, acc[0][0]); acc[0][1] = MFMA32(a0, b1, acc[0][1]);
;         acc[1][0] = MFMA32(a1, b0, acc[1][0]); acc[1][1] = MFMA32(a1, b1, acc[1][1]);
;       }
;     }
;     __builtin_amdgcn_sched_barrier(0);
;     if (more) GM_LSTORE((kt + 1) & 1)
;     __syncthreads();
;   }
	ds_read_b128 v[128:131], v172 offset:0
	ds_read_b128 v[120:123], v168 offset:0
	ds_read_b128 v[132:135], v172 offset:4096
	ds_read_b128 v[124:127], v168 offset:4096
	ds_read_b128 v[144:147], v173 offset:0
	ds_read_b128 v[136:139], v169 offset:0
	ds_read_b128 v[148:151], v173 offset:4096
	ds_read_b128 v[140:143], v169 offset:4096
	s_waitcnt lgkmcnt(4)
	v_mfma_f32_32x32x16_bf16 v[0:15], v[120:123], v[128:131], 0
	ds_read_b128 v[160:163], v174 offset:0
	v_mfma_f32_32x32x16_bf16 v[16:31], v[120:123], v[132:135], 0
	ds_read_b128 v[152:155], v170 offset:0
	v_mfma_f32_32x32x16_bf16 v[32:47], v[124:127], v[128:131], 0
	ds_read_b128 v[164:167], v174 offset:4096
	v_mfma_f32_32x32x16_bf16 v[48:63], v[124:127], v[132:135], 0
	ds_read_b128 v[156:159], v170 offset:4096
	ds_read_b128 v[128:131], v175 offset:0
	ds_read_b128 v[120:123], v171 offset:0
	ds_read_b128 v[132:135], v175 offset:4096
	ds_read_b128 v[124:127], v171 offset:4096
	s_waitcnt lgkmcnt(8)
	v_mfma_f32_32x32x16_bf16 v[0:15], v[136:139], v[144:147], v[0:15]
	v_mfma_f32_32x32x16_bf16 v[16:31], v[136:139], v[148:151], v[16:31]
	v_mfma_f32_32x32x16_bf16 v[32:47], v[140:143], v[144:147], v[32:47]
	v_mfma_f32_32x32x16_bf16 v[48:63], v[140:143], v[148:151], v[48:63]
	s_waitcnt vmcnt(22) lgkmcnt(0)
	s_barrier
	v_mfma_f32_32x32x16_bf16 v[0:15], v[152:155], v[160:163], v[0:15]
	ds_read_b128 v[144:147], v172 offset:32768
	v_mfma_f32_32x32x16_bf16 v[16:31], v[152:155], v[164:167], v[16:31]
	ds_read_b128 v[136:139], v168 offset:16384
	s_mov_b32 m0, s50
	s_nop 0
	global_load_lds_dwordx4 v180, s[46:47]
	v_mfma_f32_32x32x16_bf16 v[32:47], v[156:159], v[160:163], v[32:47]
	ds_read_b128 v[148:151], v172 offset:36864
	v_mfma_f32_32x32x16_bf16 v[48:63], v[156:159], v[164:167], v[48:63]
	ds_read_b128 v[140:143], v168 offset:20480
	global_load_lds_dwordx4 v181, s[46:47] offset:1024
	s_add_u32 s46, s46, 0x80
	s_addc_u32 s47, s47, 0
	v_mfma_f32_32x32x16_bf16 v[0:15], v[120:123], v[128:131], v[0:15]
	ds_read_b128 v[160:163], v173 offset:32768
	v_mfma_f32_32x32x16_bf16 v[16:31], v[120:123], v[132:135], v[16:31]
	ds_read_b128 v[152:155], v169 offset:16384
	s_mov_b32 m0, s51
	s_nop 0
	global_load_lds_dwordx4 v182, s[48:49]
	v_mfma_f32_32x32x16_bf16 v[32:47], v[124:127], v[128:131], v[32:47]
	ds_read_b128 v[164:167], v173 offset:36864
	v_mfma_f32_32x32x16_bf16 v[48:63], v[124:127], v[132:135], v[48:63]
	ds_read_b128 v[156:159], v169 offset:20480
	global_load_lds_dwordx4 v183, s[48:49] offset:1024
	s_waitcnt lgkmcnt(4)
	v_mfma_f32_32x32x16_bf16 v[0:15], v[136:139], v[144:147], v[0:15]
	ds_read_b128 v[128:131], v174 offset:32768
	v_mfma_f32_32x32x16_bf16 v[16:31], v[136:139], v[148:151], v[16:31]
	ds_read_b128 v[120:123], v170 offset:16384
	global_load_lds_dwordx4 v184, s[48:49] offset:2048
	v_mfma_f32_32x32x16_bf16 v[32:47], v[140:143], v[144:147], v[32:47]
	ds_read_b128 v[132:135], v174 offset:36864
	v_mfma_f32_32x32x16_bf16 v[48:63], v[140:143], v[148:151], v[48:63]
	ds_read_b128 v[124:127], v170 offset:20480
	global_load_lds_dwordx4 v185, s[48:49] offset:3072
	s_add_u32 s48, s48, 0x80
	s_addc_u32 s49, s49, 0
	ds_read_b128 v[144:147], v175 offset:32768
	ds_read_b128 v[136:139], v171 offset:16384
	ds_read_b128 v[148:151], v175 offset:36864
	ds_read_b128 v[140:143], v171 offset:20480
	s_waitcnt lgkmcnt(8)
	v_mfma_f32_32x32x16_bf16 v[0:15], v[152:155], v[160:163], v[0:15]
	v_mfma_f32_32x32x16_bf16 v[16:31], v[152:155], v[164:167], v[16:31]
	v_mfma_f32_32x32x16_bf16 v[32:47], v[156:159], v[160:163], v[32:47]
	v_mfma_f32_32x32x16_bf16 v[48:63], v[156:159], v[164:167], v[48:63]
	s_waitcnt vmcnt(22) lgkmcnt(0)
	s_barrier
	v_mfma_f32_32x32x16_bf16 v[0:15], v[120:123], v[128:131], v[0:15]
	ds_read_b128 v[160:163], v176 offset:0
	v_mfma_f32_32x32x16_bf16 v[16:31], v[120:123], v[132:135], v[16:31]
	ds_read_b128 v[152:155], v168 offset:32768
	s_add_u32 m0, s50, 0x4000
	s_nop 0
	global_load_lds_dwordx4 v180, s[46:47]
	v_mfma_f32_32x32x16_bf16 v[32:47], v[124:127], v[128:131], v[32:47]
	ds_read_b128 v[164:167], v176 offset:4096
	v_mfma_f32_32x32x16_bf16 v[48:63], v[124:127], v[132:135], v[48:63]
	ds_read_b128 v[156:159], v168 offset:36864
	global_load_lds_dwordx4 v181, s[46:47] offset:1024
	s_add_u32 s46, s46, 0x80
	s_addc_u32 s47, s47, 0
	v_mfma_f32_32x32x16_bf16 v[0:15], v[136:139], v[144:147], v[0:15]
	ds_read_b128 v[128:131], v177 offset:0
	v_mfma_f32_32x32x16_bf16 v[16:31], v[136:139], v[148:151], v[16:31]
	ds_read_b128 v[120:123], v169 offset:32768
	s_add_u32 m0, s51, 0x8000
	s_nop 0
	global_load_lds_dwordx4 v182, s[48:49]
	v_mfma_f32_32x32x16_bf16 v[32:47], v[140:143], v[144:147], v[32:47]
	ds_read_b128 v[132:135], v177 offset:4096
	v_mfma_f32_32x32x16_bf16 v[48:63], v[140:143], v[148:151], v[48:63]
	ds_read_b128 v[124:127], v169 offset:36864
	global_load_lds_dwordx4 v183, s[48:49] offset:1024
	s_waitcnt lgkmcnt(4)
	v_mfma_f32_32x32x16_bf16 v[0:15], v[152:155], v[160:163], v[0:15]
	ds_read_b128 v[144:147], v178 offset:0
	v_mfma_f32_32x32x16_bf16 v[16:31], v[152:155], v[164:167], v[16:31]
	ds_read_b128 v[136:139], v170 offset:32768
	global_load_lds_dwordx4 v184, s[48:49] offset:2048
	v_mfma_f32_32x32x16_bf16 v[32:47], v[156:159], v[160:163], v[32:47]
	ds_read_b128 v[148:151], v178 offset:4096
	v_mfma_f32_32x32x16_bf16 v[48:63], v[156:159], v[164:167], v[48:63]
	ds_read_b128 v[140:143], v170 offset:36864
	global_load_lds_dwordx4 v185, s[48:49] offset:3072
	s_add_u32 s48, s48, 0x80
	s_addc_u32 s49, s49, 0
	ds_read_b128 v[160:163], v179 offset:0
	ds_read_b128 v[152:155], v171 offset:32768
	ds_read_b128 v[164:167], v179 offset:4096
	ds_read_b128 v[156:159], v171 offset:36864
	s_waitcnt lgkmcnt(8)
	v_mfma_f32_32x32x16_bf16 v[0:15], v[120:123], v[128:131], v[0:15]
	v_mfma_f32_32x32x16_bf16 v[16:31], v[120:123], v[132:135], v[16:31]
	v_mfma_f32_32x32x16_bf16 v[32:47], v[124:127], v[128:131], v[32:47]
	v_mfma_f32_32x32x16_bf16 v[48:63], v[124:127], v[132:135], v[48:63]
	s_waitcnt vmcnt(6) lgkmcnt(0)
	s_barrier
; #define MFMA32(a, b, c) __builtin_amdgcn_mfma_f32_32x32x16_bf16((a), (b), (c), 0, 0, 0)
; DI void gemm_mid(const bf16_t* __restrict__ W, int ldw, const bf16_t* __restrict__ X, size_t ldx, int mclamp, int kts,
;                  int nkt, int m0, f32x16 (&acc)[2][2], bf16_t* lds) {
;     ...
;   for (int kt = 0; kt < nkt; ++kt) {
;     const bool more = kt + 1 < nkt;
;     if (more) GM_GLOAD(kt + 1)
;     __builtin_amdgcn_sched_barrier(0);
;     {
;       const bf16_t* wb = lds + (kt & 1) * MID_E + (wn * 64 + lr) * LDT + lh * 8;
;       const bf16_t* xb = lds + (kt & 1) * MID_E + 128 * LDT + (wm * 64 + lr) * LDT + lh * 8;
; #pragma unroll
;       for (int ks = 0; ks < 4; ++ks) {
;         const bf16x8 a0 = *(const bf16x8*)(wb + ks * 16), a1 = *(const bf16x8*)(wb + 32 * LDT + ks * 16);
;         const bf16x8 b0 = *(const bf16x8*)(xb + ks * 16), b1 = *(const bf16x8*)(xb + 32 * LDT + ks * 16);
;         acc[0][0] = MFMA32(a0, b0, acc[0][0]); acc[0][1] = MFMA32(a0, b1, acc[0][1]);
;         acc[1][0] = MFMA32(a1, b0, acc[1][0]); acc[1][1] = MFMA32(a1, b1, acc[1][1]);
;       }
;     }
;     __builtin_amdgcn_sched_barrier(0);
;     if (more) GM_LSTORE((kt + 1) & 1)
;     __syncthreads();
;   }
	v_mfma_f32_32x32x16_bf16 v[0:15], v[136:139], v[144:147], v[0:15]
	ds_read_b128 v[128:131], v172 offset:0
	v_mfma_f32_32x32x16_bf16 v[16:31], v[136:139], v[148:151], v[16:31]
	ds_read_b128 v[120:123], v168 offset:0
	s_add_u32 m0, s50, 0x8000
	s_nop 0
	global_load_lds_dwordx4 v180, s[46:47]
	v_mfma_f32_32x32x16_bf16 v[32:47], v[140:143], v[144:147], v[32:47]
	ds_read_b128 v[132:135], v172 offset:4096
	v_mfma_f32_32x32x16_bf16 v[48:63], v[140:143], v[148:151], v[48:63]
	ds_read_b128 v[124:127], v168 offset:4096
	global_load_lds_dwordx4 v181, s[46:47] offset:1024
	s_add_u32 s46, s46, 0x80
	s_addc_u32 s47, s47, 0
	v_mfma_f32_32x32x16_bf16 v[0:15], v[152:155], v[160:163], v[0:15]
	ds_read_b128 v[144:147], v173 offset:0
	v_mfma_f32_32x32x16_bf16 v[16:31], v[152:155], v[164:167], v[16:31]
	ds_read_b128 v[136:139], v169 offset:0
	s_add_u32 m0, s51, 0x10000
	s_nop 0
	global_load_lds_dwordx4 v182, s[48:49]
	v_mfma_f32_32x32x16_bf16 v[32:47], v[156:159], v[160:163], v[32:47]
	ds_read_b128 v[148:151], v173 offset:4096
	v_mfma_f32_32x32x16_bf16 v[48:63], v[156:159], v[164:167], v[48:63]
	ds_read_b128 v[140:143], v169 offset:4096
	global_load_lds_dwordx4 v183, s[48:49] offset:1024
	s_waitcnt lgkmcnt(4)
	v_mfma_f32_32x32x16_bf16 v[0:15], v[120:123], v[128:131], v[0:15]
	ds_read_b128 v[160:163], v174 offset:0
	v_mfma_f32_32x32x16_bf16 v[16:31], v[120:123], v[132:135], v[16:31]
	ds_read_b128 v[152:155], v170 offset:0
	global_load_lds_dwordx4 v184, s[48:49] offset:2048
	v_mfma_f32_32x32x16_bf16 v[32:47], v[124:127], v[128:131], v[32:47]
	ds_read_b128 v[164:167], v174 offset:4096
	v_mfma_f32_32x32x16_bf16 v[48:63], v[124:127], v[132:135], v[48:63]
	ds_read_b128 v[156:159], v170 offset:4096
	global_load_lds_dwordx4 v185, s[48:49] offset:3072
	s_add_u32 s48, s48, 0x80
	s_addc_u32 s49, s49, 0
	ds_read_b128 v[128:131], v175 offset:0
	ds_read_b128 v[120:123], v171 offset:0
	ds_read_b128 v[132:135], v175 offset:4096
	ds_read_b128 v[124:127], v171 offset:4096
	s_waitcnt lgkmcnt(8)
	v_mfma_f32_32x32x16_bf16 v[0:15], v[136:139], v[144:147], v[0:15]
	v_mfma_f32_32x32x16_bf16 v[16:31], v[136:139], v[148:151], v[16:31]
	v_mfma_f32_32x32x16_bf16 v[32:47], v[140:143], v[144:147], v[32:47]
	v_mfma_f32_32x32x16_bf16 v[48:63], v[140:143], v[148:151], v[48:63]
	s_waitcnt vmcnt(6) lgkmcnt(0)
	s_barrier
	v_mfma_f32_32x32x16_bf16 v[0:15], v[152:155], v[160:163], v[0:15]
	ds_read_b128 v[144:147], v172 offset:32768
	v_mfma_f32_32x32x16_bf16 v[16:31], v[152:155], v[164:167], v[16:31]
	ds_read_b128 v[136:139], v168 offset:16384
	s_mov_b32 m0, s50
	s_nop 0
	global_load_lds_dwordx4 v180, s[46:47]
	v_mfma_f32_32x32x16_bf16 v[32:47], v[156:159], v[160:163], v[32:47]
	ds_read_b128 v[148:151], v172 offset:36864
	v_mfma_f32_32x32x16_bf16 v[48:63], v[156:159], v[164:167], v[48:63]
	ds_read_b128 v[140:143], v168 offset:20480
	global_load_lds_dwordx4 v181, s[46:47] offset:1024
	s_add_u32 s46, s46, 0x80
	s_addc_u32 s47, s47, 0
	v_mfma_f32_32x32x16_bf16 v[0:15], v[120:123], v[128:131], v[0:15]
	ds_read_b128 v[160:163], v173 offset:32768
	v_mfma_f32_32x32x16_bf16 v[16:31], v[120:123], v[132:135], v[16:31]
	ds_read_b128 v[152:155], v169 offset:16384
	s_mov_b32 m0, s51
	s_nop 0
	global_load_lds_dwordx4 v182, s[48:49]
	v_mfma_f32_32x32x16_bf16 v[32:47], v[124:127], v[128:131], v[32:47]
	ds_read_b128 v[164:167], v173 offset:36864
	v_mfma_f32_32x32x16_bf16 v[48:63], v[124:127], v[132:135], v[48:63]
	ds_read_b128 v[156:159], v169 offset:20480
	global_load_lds_dwordx4 v183, s[48:49] offset:1024
	s_waitcnt lgkmcnt(4)
	v_mfma_f32_32x32x16_bf16 v[0:15], v[136:139], v[144:147], v[0:15]
	ds_read_b128 v[128:131], v174 offset:32768
	v_mfma_f32_32x32x16_bf16 v[16:31], v[136:139], v[148:151], v[16:31]
	ds_read_b128 v[120:123], v170 offset:16384
	global_load_lds_dwordx4 v184, s[48:49] offset:2048
	v_mfma_f32_32x32x16_bf16 v[32:47], v[140:143], v[144:147], v[32:47]
	ds_read_b128 v[132:135], v174 offset:36864
	v_mfma_f32_32x32x16_bf16 v[48:63], v[140:143], v[148:151], v[48:63]
	ds_read_b128 v[124:127], v170 offset:20480
	global_load_lds_dwordx4 v185, s[48:49] offset:3072
	s_add_u32 s48, s48, 0x80
	s_addc_u32 s49, s49, 0
	ds_read_b128 v[144:147], v175 offset:32768
	ds_read_b128 v[136:139], v171 offset:16384
	ds_read_b128 v[148:151], v175 offset:36864
	ds_read_b128 v[140:143], v171 offset:20480
	s_waitcnt lgkmcnt(8)
	v_mfma_f32_32x32x16_bf16 v[0:15], v[152:155], v[160:163], v[0:15]
	v_mfma_f32_32x32x16_bf16 v[16:31], v[152:155], v[164:167], v[16:31]
	v_mfma_f32_32x32x16_bf16 v[32:47], v[156:159], v[160:163], v[32:47]
	v_mfma_f32_32x32x16_bf16 v[48:63], v[156:159], v[164:167], v[48:63]
	s_waitcnt vmcnt(6) lgkmcnt(0)
	s_barrier
; #define MFMA32(a, b, c) __builtin_amdgcn_mfma_f32_32x32x16_bf16((a), (b), (c), 0, 0, 0)
; DI void gemm_mid(const bf16_t* __restrict__ W, int ldw, const bf16_t* __restrict__ X, size_t ldx, int mclamp, int kts,
;                  int nkt, int m0, f32x16 (&acc)[2][2], bf16_t* lds) {
;     ...
;   for (int kt = 0; kt < nkt; ++kt) {
;     const bool more = kt + 1 < nkt;
;     if (more) GM_GLOAD(kt + 1)
;     __builtin_amdgcn_sched_barrier(0);
;     {
;       const bf16_t* wb = lds + (kt & 1) * MID_E + (wn * 64 + lr) * LDT + lh * 8;
;       const bf16_t* xb = lds + (kt & 1) * MID_E + 128 * LDT + (wm * 64 + lr) * LDT + lh * 8;
; #pragma unroll
;       for (int ks = 0; ks < 4; ++ks) {
;         const bf16x8 a0 = *(const bf16x8*)(wb + ks * 16), a1 = *(const bf16x8*)(wb + 32 * LDT + ks * 16);
;         const bf16x8 b0 = *(const bf16x8*)(xb + ks * 16), b1 = *(const bf16x8*)(xb + 32 * LDT + ks * 16);
;         acc[0][0] = MFMA32(a0, b0, acc[0][0]); acc[0][1] = MFMA32(a0, b1, acc[0][1]);
;         acc[1][0] = MFMA32(a1, b0, acc[1][0]); acc[1][1] = MFMA32(a1, b1, acc[1][1]);
;       }
;     }
;     __builtin_amdgcn_sched_barrier(0);
;     if (more) GM_LSTORE((kt + 1) & 1)
;     __syncthreads();
;   }
	v_mfma_f32_32x32x16_bf16 v[0:15], v[120:123], v[128:131], v[0:15]
	ds_read_b128 v[160:163], v176 offset:0
	v_mfma_f32_32x32x16_bf16 v[16:31], v[120:123], v[132:135], v[16:31]
	ds_read_b128 v[152:155], v168 offset:32768
	s_add_u32 m0, s50, 0x4000
	s_nop 0
	global_load_lds_dwordx4 v180, s[46:47]
	v_mfma_f32_32x32x16_bf16 v[32:47], v[124:127], v[128:131], v[32:47]
	ds_read_b128 v[164:167], v176 offset:4096
	v_mfma_f32_32x32x16_bf16 v[48:63], v[124:127], v[132:135], v[48:63]
	ds_read_b128 v[156:159], v168 offset:36864
	global_load_lds_dwordx4 v181, s[46:47] offset:1024
	s_add_u32 s46, s46, 0x80
	s_addc_u32 s47, s47, 0
	v_mfma_f32_32x32x16_bf16 v[0:15], v[136:139], v[144:147], v[0:15]
	ds_read_b128 v[128:131], v177 offset:0
	v_mfma_f32_32x32x16_bf16 v[16:31], v[136:139], v[148:151], v[16:31]
	ds_read_b128 v[120:123], v169 offset:32768
	s_add_u32 m0, s51, 0x8000
	s_nop 0
	global_load_lds_dwordx4 v182, s[48:49]
	v_mfma_f32_32x32x16_bf16 v[32:47], v[140:143], v[144:147], v[32:47]
	ds_read_b128 v[132:135], v177 offset:4096
	v_mfma_f32_32x32x16_bf16 v[48:63], v[140:143], v[148:151], v[48:63]
	ds_read_b128 v[124:127], v169 offset:36864
	global_load_lds_dwordx4 v183, s[48:49] offset:1024
	s_waitcnt lgkmcnt(4)
	v_mfma_f32_32x32x16_bf16 v[0:15], v[152:155], v[160:163], v[0:15]
	ds_read_b128 v[144:147], v178 offset:0
	v_mfma_f32_32x32x16_bf16 v[16:31], v[152:155], v[164:167], v[16:31]
	ds_read_b128 v[136:139], v170 offset:32768
	global_load_lds_dwordx4 v184, s[48:49] offset:2048
	v_mfma_f32_32x32x16_bf16 v[32:47], v[156:159], v[160:163], v[32:47]
	ds_read_b128 v[148:151], v178 offset:4096
	v_mfma_f32_32x32x16_bf16 v[48:63], v[156:159], v[164:167], v[48:63]
	ds_read_b128 v[140:143], v170 offset:36864
	global_load_lds_dwordx4 v185, s[48:49] offset:3072
	s_add_u32 s48, s48, 0x80
	s_addc_u32 s49, s49, 0
	ds_read_b128 v[160:163], v179 offset:0
	ds_read_b128 v[152:155], v171 offset:32768
	ds_read_b128 v[164:167], v179 offset:4096
	ds_read_b128 v[156:159], v171 offset:36864
	s_waitcnt lgkmcnt(8)
	v_mfma_f32_32x32x16_bf16 v[0:15], v[120:123], v[128:131], v[0:15]
	v_mfma_f32_32x32x16_bf16 v[16:31], v[120:123], v[132:135], v[16:31]
	v_mfma_f32_32x32x16_bf16 v[32:47], v[124:127], v[128:131], v[32:47]
	v_mfma_f32_32x32x16_bf16 v[48:63], v[124:127], v[132:135], v[48:63]
	s_waitcnt vmcnt(6) lgkmcnt(0)
	s_barrier
	v_mfma_f32_32x32x16_bf16 v[0:15], v[136:139], v[144:147], v[0:15]
	ds_read_b128 v[128:131], v172 offset:0
	v_mfma_f32_32x32x16_bf16 v[16:31], v[136:139], v[148:151], v[16:31]
	ds_read_b128 v[120:123], v168 offset:0
	v_mfma_f32_32x32x16_bf16 v[32:47], v[140:143], v[144:147], v[32:47]
	ds_read_b128 v[132:135], v172 offset:4096
	v_mfma_f32_32x32x16_bf16 v[48:63], v[140:143], v[148:151], v[48:63]
	ds_read_b128 v[124:127], v168 offset:4096
	v_mfma_f32_32x32x16_bf16 v[0:15], v[152:155], v[160:163], v[0:15]
	ds_read_b128 v[144:147], v173 offset:0
	v_mfma_f32_32x32x16_bf16 v[16:31], v[152:155], v[164:167], v[16:31]
	ds_read_b128 v[136:139], v169 offset:0
	v_mfma_f32_32x32x16_bf16 v[32:47], v[156:159], v[160:163], v[32:47]
	ds_read_b128 v[148:151], v173 offset:4096
	v_mfma_f32_32x32x16_bf16 v[48:63], v[156:159], v[164:167], v[48:63]
	ds_read_b128 v[140:143], v169 offset:4096
	s_waitcnt lgkmcnt(4)
	v_mfma_f32_32x32x16_bf16 v[0:15], v[120:123], v[128:131], v[0:15]
	ds_read_b128 v[160:163], v174 offset:0
	v_mfma_f32_32x32x16_bf16 v[16:31], v[120:123], v[132:135], v[16:31]
	ds_read_b128 v[152:155], v170 offset:0
	v_mfma_f32_32x32x16_bf16 v[32:47], v[124:127], v[128:131], v[32:47]
	ds_read_b128 v[164:167], v174 offset:4096
	v_mfma_f32_32x32x16_bf16 v[48:63], v[124:127], v[132:135], v[48:63]
	ds_read_b128 v[156:159], v170 offset:4096
	ds_read_b128 v[128:131], v175 offset:0
	ds_read_b128 v[120:123], v171 offset:0
	ds_read_b128 v[132:135], v175 offset:4096
	ds_read_b128 v[124:127], v171 offset:4096
	s_waitcnt lgkmcnt(8)
	v_mfma_f32_32x32x16_bf16 v[0:15], v[136:139], v[144:147], v[0:15]
	v_mfma_f32_32x32x16_bf16 v[16:31], v[136:139], v[148:151], v[16:31]
	v_mfma_f32_32x32x16_bf16 v[32:47], v[140:143], v[144:147], v[32:47]
	v_mfma_f32_32x32x16_bf16 v[48:63], v[140:143], v[148:151], v[48:63]
	s_waitcnt vmcnt(0) lgkmcnt(0)
	s_barrier
	v_mfma_f32_32x32x16_bf16 v[0:15], v[152:155], v[160:163], v[0:15]
	ds_read_b128 v[144:147], v172 offset:32768
	v_mfma_f32_32x32x16_bf16 v[16:31], v[152:155], v[164:167], v[16:31]
	ds_read_b128 v[136:139], v168 offset:16384
	v_mfma_f32_32x32x16_bf16 v[32:47], v[156:159], v[160:163], v[32:47]
	ds_read_b128 v[148:151], v172 offset:36864
	v_mfma_f32_32x32x16_bf16 v[48:63], v[156:159], v[164:167], v[48:63]
	ds_read_b128 v[140:143], v168 offset:20480
	v_mfma_f32_32x32x16_bf16 v[0:15], v[120:123], v[128:131], v[0:15]
	ds_read_b128 v[160:163], v173 offset:32768
	v_mfma_f32_32x32x16_bf16 v[16:31], v[120:123], v[132:135], v[16:31]
	ds_read_b128 v[152:155], v169 offset:16384
	v_mfma_f32_32x32x16_bf16 v[32:47], v[124:127], v[128:131], v[32:47]
	ds_read_b128 v[164:167], v173 offset:36864
	v_mfma_f32_32x32x16_bf16 v[48:63], v[124:127], v[132:135], v[48:63]
	ds_read_b128 v[156:159], v169 offset:20480
	s_waitcnt lgkmcnt(4)
	v_mfma_f32_32x32x16_bf16 v[0:15], v[136:139], v[144:147], v[0:15]
	ds_read_b128 v[128:131], v174 offset:32768
	v_mfma_f32_32x32x16_bf16 v[16:31], v[136:139], v[148:151], v[16:31]
	ds_read_b128 v[120:123], v170 offset:16384
	v_mfma_f32_32x32x16_bf16 v[32:47], v[140:143], v[144:147], v[32:47]
	ds_read_b128 v[132:135], v174 offset:36864
	v_mfma_f32_32x32x16_bf16 v[48:63], v[140:143], v[148:151], v[48:63]
	ds_read_b128 v[124:127], v170 offset:20480
	ds_read_b128 v[144:147], v175 offset:32768
	ds_read_b128 v[136:139], v171 offset:16384
	ds_read_b128 v[148:151], v175 offset:36864
	ds_read_b128 v[140:143], v171 offset:20480
	s_waitcnt lgkmcnt(8)
	v_mfma_f32_32x32x16_bf16 v[0:15], v[152:155], v[160:163], v[0:15]
	v_mfma_f32_32x32x16_bf16 v[16:31], v[152:155], v[164:167], v[16:31]
	v_mfma_f32_32x32x16_bf16 v[32:47], v[156:159], v[160:163], v[32:47]
	v_mfma_f32_32x32x16_bf16 v[48:63], v[156:159], v[164:167], v[48:63]
	s_waitcnt lgkmcnt(0)
	s_barrier
; DI void gemm_mid(const bf16_t* __restrict__ W, int ldw, const bf16_t* __restrict__ X, size_t ldx, int mclamp, int kts,
;                  int nkt, int m0, f32x16 (&acc)[2][2], bf16_t* lds) {
;     ...
;   for (int kt = 0; kt < nkt; ++kt) {
;     const bool more = kt + 1 < nkt;
;     if (more) GM_GLOAD(kt + 1)
;     __builtin_amdgcn_sched_barrier(0);
;     {
;       const bf16_t* wb = lds + (kt & 1) * MID_E + (wn * 64 + lr) * LDT + lh * 8;
;       const bf16_t* xb = lds + (kt & 1) * MID_E + 128 * LDT + (wm * 64 + lr) * LDT + lh * 8;
; #pragma unroll
;       for (int ks = 0; ks < 4; ++ks) {
;         const bf16x8 a0 = *(const bf16x8*)(wb + ks * 16), a1 = *(const bf16x8*)(wb + 32 * LDT + ks * 16);
;         const bf16x8 b0 = *(const bf16x8*)(xb + ks * 16), b1 = *(const bf16x8*)(xb + 32 * LDT + ks * 16);
;         acc[0][0] = MFMA32(a0, b0, acc[0][0]); acc[0][1] = MFMA32(a0, b1, acc[0][1]);
;         acc[1][0] = MFMA32(a1, b0, acc[1][0]); acc[1][1] = MFMA32(a1, b1, acc[1][1]);
;       }
;     }
;     __builtin_amdgcn_sched_barrier(0);
;     if (more) GM_LSTORE((kt + 1) & 1)
;     __syncthreads();
;   }
; DI void phase_merge(const P& p, int layer, bf16_t* sm, const Geo& ge) {
;     ...
;     for (int n3 = 0; n3 < 3; ++n3) {
;       const bf16_t* X = (const bf16_t*)(p.ws + (n3 == 0 ? O_AQ : (n3 == 1 ? O_BQ : O_CQ)));
;       f32x16 acc[2][2]; zero_acc(acc);
;       gemm_mid(W + ((size_t)n3 * 1024 + nt_ * 128) * 512, 512, X, 512, 1 << 30, 64, 8, mt_ * 256, acc, sm);
; #pragma unroll
;       for (int mt = 0; mt < 2; ++mt) {
;         const int m = mt_ * 256 + wm * 64 + mt * 32 + lr;
; #pragma unroll
;         for (int nt = 0; nt < 2; ++nt)
; #pragma unroll
;           for (int qd = 0; qd < 4; ++qd) {
;             const int n = nt_ * 128 + wn * 64 + nt * 32 + 8 * qd + 4 * lh;
;             typedef unsigned u32x2_t __attribute__((ext_vector_type(2)));
;             const u32x2_t gq_ = __builtin_nontemporal_load((const u32x2_t*)(mgs + ((size_t)((n3 * 1024 + n) >> 2) * T_ + m) * 4));
;             const uint2 gq = make_uint2(gq_[0], gq_[1]);
;             const unsigned z01 = zp[nt][mt][2 * qd], z23 = zp[nt][mt][2 * qd + 1];
;             const float v0 = bf2f((bf16_t)(z01 & 0xffff)) + bf2f((bf16_t)(gq.x & 0xffff)) * acc[nt][mt][4 * qd];
;             const float v1 = bf2f((bf16_t)(z01 >> 16)) + bf2f((bf16_t)(gq.x >> 16)) * acc[nt][mt][4 * qd + 1];
	v_mfma_f32_32x32x16_bf16 v[0:15], v[120:123], v[128:131], v[0:15]
	v_mfma_f32_32x32x16_bf16 v[16:31], v[120:123], v[132:135], v[16:31]
	v_mfma_f32_32x32x16_bf16 v[32:47], v[124:127], v[128:131], v[32:47]
	v_mfma_f32_32x32x16_bf16 v[48:63], v[124:127], v[132:135], v[48:63]
	v_mfma_f32_32x32x16_bf16 v[0:15], v[136:139], v[144:147], v[0:15]
	v_mfma_f32_32x32x16_bf16 v[16:31], v[136:139], v[148:151], v[16:31]
	v_mfma_f32_32x32x16_bf16 v[32:47], v[140:143], v[144:147], v[32:47]
	v_mfma_f32_32x32x16_bf16 v[48:63], v[140:143], v[148:151], v[48:63]
	s_add_u32 s46, s46, 0xffc00
	s_addc_u32 s47, s47, 0
	s_add_u32 s48, s48, 0xfffc00
	s_addc_u32 s49, s49, 0
	s_mov_b32 m0, s50
	s_nop 0
	global_load_lds_dwordx4 v180, s[46:47]
	global_load_lds_dwordx4 v181, s[46:47] offset:1024
	s_add_u32 s46, s46, 0x80
	s_addc_u32 s47, s47, 0
	s_mov_b32 m0, s51
	s_nop 0
	global_load_lds_dwordx4 v182, s[48:49]
	global_load_lds_dwordx4 v183, s[48:49] offset:1024
	global_load_lds_dwordx4 v184, s[48:49] offset:2048
	global_load_lds_dwordx4 v185, s[48:49] offset:3072
	s_add_u32 s48, s48, 0x80
	s_addc_u32 s49, s49, 0
	s_add_u32 m0, s50, 0x4000
	s_nop 0
	global_load_lds_dwordx4 v180, s[46:47]
	global_load_lds_dwordx4 v181, s[46:47] offset:1024
	s_add_u32 s46, s46, 0x80
	s_addc_u32 s47, s47, 0
	s_add_u32 m0, s51, 0x8000
	s_nop 0
	global_load_lds_dwordx4 v182, s[48:49]
	global_load_lds_dwordx4 v183, s[48:49] offset:1024
	global_load_lds_dwordx4 v184, s[48:49] offset:2048
	global_load_lds_dwordx4 v185, s[48:49] offset:3072
	s_add_u32 s48, s48, 0x80
	s_addc_u32 s49, s49, 0
	s_add_u32 m0, s50, 0x8000
	s_nop 0
	global_load_lds_dwordx4 v180, s[46:47]
	global_load_lds_dwordx4 v181, s[46:47] offset:1024
	s_add_u32 s46, s46, 0x80
	s_addc_u32 s47, s47, 0
	s_add_u32 m0, s51, 0x10000
	s_nop 0
	global_load_lds_dwordx4 v182, s[48:49]
	global_load_lds_dwordx4 v183, s[48:49] offset:1024
	global_load_lds_dwordx4 v184, s[48:49] offset:2048
	global_load_lds_dwordx4 v185, s[48:49] offset:3072
	s_add_u32 s48, s48, 0x80
	s_addc_u32 s49, s49, 0
	v_lshlrev_b32_e32 v98, 16, v196
	v_and_b32_e32 v99, 0xffff0000, v196
	v_lshlrev_b32_e32 v100, 16, v197
	v_and_b32_e32 v101, 0xffff0000, v197
	v_mul_f32_e32 v98, v0, v98
	v_mul_f32_e32 v99, v1, v99
	v_mul_f32_e32 v100, v2, v100
	v_mul_f32_e32 v101, v3, v101
	v_cvt_pk_bf16_f32 v64, v98, v99
	v_cvt_pk_bf16_f32 v65, v100, v101
	v_lshlrev_b32_e32 v98, 16, v198
	v_and_b32_e32 v99, 0xffff0000, v198
	v_lshlrev_b32_e32 v100, 16, v199
	v_and_b32_e32 v101, 0xffff0000, v199
	v_mul_f32_e32 v98, v4, v98
	v_mul_f32_e32 v99, v5, v99
	v_mul_f32_e32 v100, v6, v100
	v_mul_f32_e32 v101, v7, v101
	v_cvt_pk_bf16_f32 v66, v98, v99
	v_cvt_pk_bf16_f32 v67, v100, v101
	v_lshlrev_b32_e32 v98, 16, v200
	v_and_b32_e32 v99, 0xffff0000, v200
	v_lshlrev_b32_e32 v100, 16, v201
	v_and_b32_e32 v101, 0xffff0000, v201
	v_mul_f32_e32 v98, v8, v98
	v_mul_f32_e32 v99, v9, v99
	v_mul_f32_e32 v100, v10, v100
	v_mul_f32_e32 v101, v11, v101
	v_cvt_pk_bf16_f32 v68, v98, v99
	v_cvt_pk_bf16_f32 v69, v100, v101
	v_lshlrev_b32_e32 v98, 16, v202
	v_and_b32_e32 v99, 0xffff0000, v202
	v_lshlrev_b32_e32 v100, 16, v203
	v_and_b32_e32 v101, 0xffff0000, v203
	v_mul_f32_e32 v98, v12, v98
	v_mul_f32_e32 v99, v13, v99
	v_mul_f32_e32 v100, v14, v100
	v_mul_f32_e32 v101, v15, v101
	v_cvt_pk_bf16_f32 v70, v98, v99
	v_cvt_pk_bf16_f32 v71, v100, v101
	v_lshlrev_b32_e32 v98, 16, v204
	v_and_b32_e32 v99, 0xffff0000, v204
	v_lshlrev_b32_e32 v100, 16, v205
	v_and_b32_e32 v101, 0xffff0000, v205
	v_mul_f32_e32 v98, v32, v98
	v_mul_f32_e32 v99, v33, v99
	v_mul_f32_e32 v100, v34, v100
	v_mul_f32_e32 v101, v35, v101
	v_cvt_pk_bf16_f32 v72, v98, v99
	v_cvt_pk_bf16_f32 v73, v100, v101
	v_lshlrev_b32_e32 v98, 16, v206
	v_and_b32_e32 v99, 0xffff0000, v206
	v_lshlrev_b32_e32 v100, 16, v207
	v_and_b32_e32 v101, 0xffff0000, v207
	v_mul_f32_e32 v98, v36, v98
	v_mul_f32_e32 v99, v37, v99
	v_mul_f32_e32 v100, v38, v100
	v_mul_f32_e32 v101, v39, v101
	v_cvt_pk_bf16_f32 v74, v98, v99
	v_cvt_pk_bf16_f32 v75, v100, v101
	v_lshlrev_b32_e32 v98, 16, v208
	v_and_b32_e32 v99, 0xffff0000, v208
	v_lshlrev_b32_e32 v100, 16, v209
	v_and_b32_e32 v101, 0xffff0000, v209
	v_mul_f32_e32 v98, v40, v98
	v_mul_f32_e32 v99, v41, v99
	v_mul_f32_e32 v100, v42, v100
	v_mul_f32_e32 v101, v43, v101
	v_cvt_pk_bf16_f32 v76, v98, v99
	v_cvt_pk_bf16_f32 v77, v100, v101
	v_lshlrev_b32_e32 v98, 16, v210
	v_and_b32_e32 v99, 0xffff0000, v210
	v_lshlrev_b32_e32 v100, 16, v211
	v_and_b32_e32 v101, 0xffff0000, v211
	v_mul_f32_e32 v98, v44, v98
	v_mul_f32_e32 v99, v45, v99
	v_mul_f32_e32 v100, v46, v100
	v_mul_f32_e32 v101, v47, v101
	v_cvt_pk_bf16_f32 v78, v98, v99
	v_cvt_pk_bf16_f32 v79, v100, v101
	v_lshlrev_b32_e32 v98, 16, v212
	v_and_b32_e32 v99, 0xffff0000, v212
	v_lshlrev_b32_e32 v100, 16, v213
	v_and_b32_e32 v101, 0xffff0000, v213
	v_mul_f32_e32 v98, v16, v98
	v_mul_f32_e32 v99, v17, v99
	v_mul_f32_e32 v100, v18, v100
	v_mul_f32_e32 v101, v19, v101
	v_cvt_pk_bf16_f32 v80, v98, v99
	v_cvt_pk_bf16_f32 v81, v100, v101
	v_lshlrev_b32_e32 v98, 16, v214
	v_and_b32_e32 v99, 0xffff0000, v214
	v_lshlrev_b32_e32 v100, 16, v215
	v_and_b32_e32 v101, 0xffff0000, v215
	v_mul_f32_e32 v98, v20, v98
	v_mul_f32_e32 v99, v21, v99
	v_mul_f32_e32 v100, v22, v100
	v_mul_f32_e32 v101, v23, v101
	v_cvt_pk_bf16_f32 v82, v98, v99
	v_cvt_pk_bf16_f32 v83, v100, v101
	v_lshlrev_b32_e32 v98, 16, v216
	v_and_b32_e32 v99, 0xffff0000, v216
	v_lshlrev_b32_e32 v100, 16, v217
	v_and_b32_e32 v101, 0xffff0000, v217
	v_mul_f32_e32 v98, v24, v98
	v_mul_f32_e32 v99, v25, v99
	v_mul_f32_e32 v100, v26, v100
	v_mul_f32_e32 v101, v27, v101
	v_cvt_pk_bf16_f32 v84, v98, v99
	v_cvt_pk_bf16_f32 v85, v100, v101
; DI void gemm_mid(const bf16_t* __restrict__ W, int ldw, const bf16_t* __restrict__ X, size_t ldx, int mclamp, int kts,
;                  int nkt, int m0, f32x16 (&acc)[2][2], bf16_t* lds) {
;     ...
;   for (int kt = 0; kt < nkt; ++kt) {
;     const bool more = kt + 1 < nkt;
;     if (more) GM_GLOAD(kt + 1)
;     __builtin_amdgcn_sched_barrier(0);
;     {
;       const bf16_t* wb = lds + (kt & 1) * MID_E + (wn * 64 + lr) * LDT + lh * 8;
;       const bf16_t* xb = lds + (kt & 1) * MID_E + 128 * LDT + (wm * 64 + lr) * LDT + lh * 8;
; #pragma unroll
;       for (int ks = 0; ks < 4; ++ks) {
;         const bf16x8 a0 = *(const bf16x8*)(wb + ks * 16), a1 = *(const bf16x8*)(wb + 32 * LDT + ks * 16);
;         const bf16x8 b0 = *(const bf16x8*)(xb + ks * 16), b1 = *(const bf16x8*)(xb + 32 * LDT + ks * 16);
;         acc[0][0] = MFMA32(a0, b0, acc[0][0]); acc[0][1] = MFMA32(a0, b1, acc[0][1]);
;         acc[1][0] = MFMA32(a1, b0, acc[1][0]); acc[1][1] = MFMA32(a1, b1, acc[1][1]);
;       }
;     }
;     __builtin_amdgcn_sched_barrier(0);
;     if (more) GM_LSTORE((kt + 1) & 1)
; DI void phase_merge(const P& p, int layer, bf16_t* sm, const Geo& ge) {
;     ...
; #pragma unroll
;       for (int mt = 0; mt < 2; ++mt) {
;         const int m = mt_ * 256 + wm * 64 + mt * 32 + lr;
; #pragma unroll
;         for (int nt = 0; nt < 2; ++nt)
; #pragma unroll
;           for (int qd = 0; qd < 4; ++qd) {
;             const int n = nt_ * 128 + wn * 64 + nt * 32 + 8 * qd + 4 * lh;
;             typedef unsigned u32x2_t __attribute__((ext_vector_type(2)));
;             const u32x2_t gq_ = __builtin_nontemporal_load((const u32x2_t*)(mgs + ((size_t)((n3 * 1024 + n) >> 2) * T_ + m) * 4));
;             const uint2 gq = make_uint2(gq_[0], gq_[1]);
;             const unsigned z01 = zp[nt][mt][2 * qd], z23 = zp[nt][mt][2 * qd + 1];
;             const float v0 = bf2f((bf16_t)(z01 & 0xffff)) + bf2f((bf16_t)(gq.x & 0xffff)) * acc[nt][mt][4 * qd];
;             const float v1 = bf2f((bf16_t)(z01 >> 16)) + bf2f((bf16_t)(gq.x >> 16)) * acc[nt][mt][4 * qd + 1];
;             const float v2 = bf2f((bf16_t)(z23 & 0xffff)) + bf2f((bf16_t)(gq.y & 0xffff)) * acc[nt][mt][4 * qd + 2];
;             const float v3 = bf2f((bf16_t)(z23 >> 16)) + bf2f((bf16_t)(gq.y >> 16)) * acc[nt][mt][4 * qd + 3];
;             zp[nt][mt][2 * qd] = pack2(v0, v1);
;             zp[nt][mt][2 * qd + 1] = pack2(v2, v3);
;           }
	v_lshlrev_b32_e32 v98, 16, v218
	v_and_b32_e32 v99, 0xffff0000, v218
	v_lshlrev_b32_e32 v100, 16, v219
	v_and_b32_e32 v101, 0xffff0000, v219
	v_mul_f32_e32 v98, v28, v98
	v_mul_f32_e32 v99, v29, v99
	v_mul_f32_e32 v100, v30, v100
	v_mul_f32_e32 v101, v31, v101
	v_cvt_pk_bf16_f32 v86, v98, v99
	v_cvt_pk_bf16_f32 v87, v100, v101
	v_lshlrev_b32_e32 v98, 16, v236
	v_and_b32_e32 v99, 0xffff0000, v236
	v_lshlrev_b32_e32 v100, 16, v237
	v_and_b32_e32 v101, 0xffff0000, v237
	v_mul_f32_e32 v98, v48, v98
	v_mul_f32_e32 v99, v49, v99
	v_mul_f32_e32 v100, v50, v100
	v_mul_f32_e32 v101, v51, v101
	v_cvt_pk_bf16_f32 v90, v98, v99
	v_cvt_pk_bf16_f32 v91, v100, v101
	v_lshlrev_b32_e32 v98, 16, v238
	v_and_b32_e32 v99, 0xffff0000, v238
	v_lshlrev_b32_e32 v100, 16, v239
	v_and_b32_e32 v101, 0xffff0000, v239
	v_mul_f32_e32 v98, v52, v98
	v_mul_f32_e32 v99, v53, v99
	v_mul_f32_e32 v100, v54, v100
	v_mul_f32_e32 v101, v55, v101
	v_cvt_pk_bf16_f32 v92, v98, v99
	v_cvt_pk_bf16_f32 v93, v100, v101
	v_lshlrev_b32_e32 v98, 16, v240
	v_and_b32_e32 v99, 0xffff0000, v240
	v_lshlrev_b32_e32 v100, 16, v241
	v_and_b32_e32 v101, 0xffff0000, v241
	v_mul_f32_e32 v98, v56, v98
	v_mul_f32_e32 v99, v57, v99
	v_mul_f32_e32 v100, v58, v100
	v_mul_f32_e32 v101, v59, v101
	v_cvt_pk_bf16_f32 v94, v98, v99
	v_cvt_pk_bf16_f32 v95, v100, v101
	v_lshlrev_b32_e32 v98, 16, v242
	v_and_b32_e32 v99, 0xffff0000, v242
	v_lshlrev_b32_e32 v100, 16, v243
	v_and_b32_e32 v101, 0xffff0000, v243
	v_mul_f32_e32 v98, v60, v98
	v_mul_f32_e32 v99, v61, v99
	v_mul_f32_e32 v100, v62, v100
	v_mul_f32_e32 v101, v63, v101
	v_cvt_pk_bf16_f32 v96, v98, v99
	v_cvt_pk_bf16_f32 v97, v100, v101
	v_add_u32_e32 v190, 0x2000000, v186
	global_load_dwordx2 v[196:197], v190, s[28:29] nt
	global_load_dwordx2 v[212:213], v190, s[28:29] offset:256 nt
	v_add_u32_e32 v191, 0x2040000, v186
	global_load_dwordx2 v[198:199], v191, s[28:29] nt
	global_load_dwordx2 v[214:215], v191, s[28:29] offset:256 nt
	v_add_u32_e32 v190, 0x2080000, v186
	global_load_dwordx2 v[200:201], v190, s[28:29] nt
	global_load_dwordx2 v[216:217], v190, s[28:29] offset:256 nt
	v_add_u32_e32 v191, 0x20c0000, v186
	global_load_dwordx2 v[202:203], v191, s[28:29] nt
	global_load_dwordx2 v[218:219], v191, s[28:29] offset:256 nt
	v_add_u32_e32 v190, 0x2100000, v186
	global_load_dwordx2 v[204:205], v190, s[28:29] nt
	global_load_dwordx2 v[236:237], v190, s[28:29] offset:256 nt
	v_add_u32_e32 v191, 0x2140000, v186
	global_load_dwordx2 v[206:207], v191, s[28:29] nt
	global_load_dwordx2 v[238:239], v191, s[28:29] offset:256 nt
	v_add_u32_e32 v190, 0x2180000, v186
	global_load_dwordx2 v[208:209], v190, s[28:29] nt
	global_load_dwordx2 v[240:241], v190, s[28:29] offset:256 nt
	v_add_u32_e32 v191, 0x21c0000, v186
	global_load_dwordx2 v[210:211], v191, s[28:29] nt
	global_load_dwordx2 v[242:243], v191, s[28:29] offset:256 nt
	s_waitcnt vmcnt(28)
	s_barrier
	ds_read_b128 v[128:131], v172 offset:0
	ds_read_b128 v[120:123], v168 offset:0
	ds_read_b128 v[132:135], v172 offset:4096
	ds_read_b128 v[124:127], v168 offset:4096
	ds_read_b128 v[144:147], v173 offset:0
	ds_read_b128 v[136:139], v169 offset:0
	ds_read_b128 v[148:151], v173 offset:4096
	ds_read_b128 v[140:143], v169 offset:4096
	s_waitcnt lgkmcnt(4)
	v_mfma_f32_32x32x16_bf16 v[0:15], v[120:123], v[128:131], 0
	ds_read_b128 v[160:163], v174 offset:0
	v_mfma_f32_32x32x16_bf16 v[16:31], v[120:123], v[132:135], 0
	ds_read_b128 v[152:155], v170 offset:0
	v_mfma_f32_32x32x16_bf16 v[32:47], v[124:127], v[128:131], 0
	ds_read_b128 v[164:167], v174 offset:4096
	v_mfma_f32_32x32x16_bf16 v[48:63], v[124:127], v[132:135], 0
	ds_read_b128 v[156:159], v170 offset:4096
	ds_read_b128 v[128:131], v175 offset:0
	ds_read_b128 v[120:123], v171 offset:0
	ds_read_b128 v[132:135], v175 offset:4096
	ds_read_b128 v[124:127], v171 offset:4096
	s_waitcnt lgkmcnt(8)
	v_mfma_f32_32x32x16_bf16 v[0:15], v[136:139], v[144:147], v[0:15]
	v_mfma_f32_32x32x16_bf16 v[16:31], v[136:139], v[148:151], v[16:31]
	v_mfma_f32_32x32x16_bf16 v[32:47], v[140:143], v[144:147], v[32:47]
	v_mfma_f32_32x32x16_bf16 v[48:63], v[140:143], v[148:151], v[48:63]
	s_waitcnt vmcnt(22) lgkmcnt(0)
	s_barrier
	v_mfma_f32_32x32x16_bf16 v[0:15], v[152:155], v[160:163], v[0:15]
	ds_read_b128 v[144:147], v172 offset:32768
	v_mfma_f32_32x32x16_bf16 v[16:31], v[152:155], v[164:167], v[16:31]
	ds_read_b128 v[136:139], v168 offset:16384
	s_mov_b32 m0, s50
	s_nop 0
	global_load_lds_dwordx4 v180, s[46:47]
	v_mfma_f32_32x32x16_bf16 v[32:47], v[156:159], v[160:163], v[32:47]
	ds_read_b128 v[148:151], v172 offset:36864
	v_mfma_f32_32x32x16_bf16 v[48:63], v[156:159], v[164:167], v[48:63]
	ds_read_b128 v[140:143], v168 offset:20480
	global_load_lds_dwordx4 v181, s[46:47] offset:1024
	s_add_u32 s46, s46, 0x80
	s_addc_u32 s47, s47, 0
	v_mfma_f32_32x32x16_bf16 v[0:15], v[120:123], v[128:131], v[0:15]
	ds_read_b128 v[160:163], v173 offset:32768
	v_mfma_f32_32x32x16_bf16 v[16:31], v[120:123], v[132:135], v[16:31]
	ds_read_b128 v[152:155], v169 offset:16384
	s_mov_b32 m0, s51
	s_nop 0
	global_load_lds_dwordx4 v182, s[48:49]
	v_mfma_f32_32x32x16_bf16 v[32:47], v[124:127], v[128:131], v[32:47]
	ds_read_b128 v[164:167], v173 offset:36864
	v_mfma_f32_32x32x16_bf16 v[48:63], v[124:127], v[132:135], v[48:63]
	ds_read_b128 v[156:159], v169 offset:20480
	global_load_lds_dwordx4 v183, s[48:49] offset:1024
	s_waitcnt lgkmcnt(4)
	v_mfma_f32_32x32x16_bf16 v[0:15], v[136:139], v[144:147], v[0:15]
	ds_read_b128 v[128:131], v174 offset:32768
	v_mfma_f32_32x32x16_bf16 v[16:31], v[136:139], v[148:151], v[16:31]
	ds_read_b128 v[120:123], v170 offset:16384
	global_load_lds_dwordx4 v184, s[48:49] offset:2048
	v_mfma_f32_32x32x16_bf16 v[32:47], v[140:143], v[144:147], v[32:47]
	ds_read_b128 v[132:135], v174 offset:36864
	v_mfma_f32_32x32x16_bf16 v[48:63], v[140:143], v[148:151], v[48:63]
	ds_read_b128 v[124:127], v170 offset:20480
	global_load_lds_dwordx4 v185, s[48:49] offset:3072
	s_add_u32 s48, s48, 0x80
	s_addc_u32 s49, s49, 0
	ds_read_b128 v[144:147], v175 offset:32768
	ds_read_b128 v[136:139], v171 offset:16384
	ds_read_b128 v[148:151], v175 offset:36864
	ds_read_b128 v[140:143], v171 offset:20480
	s_waitcnt lgkmcnt(8)
	v_mfma_f32_32x32x16_bf16 v[0:15], v[152:155], v[160:163], v[0:15]
	v_mfma_f32_32x32x16_bf16 v[16:31], v[152:155], v[164:167], v[16:31]
	v_mfma_f32_32x32x16_bf16 v[32:47], v[156:159], v[160:163], v[32:47]
	v_mfma_f32_32x32x16_bf16 v[48:63], v[156:159], v[164:167], v[48:63]
	s_waitcnt vmcnt(22) lgkmcnt(0)
	s_barrier
; #define MFMA32(a, b, c) __builtin_amdgcn_mfma_f32_32x32x16_bf16((a), (b), (c), 0, 0, 0)
; DI void gemm_mid(const bf16_t* __restrict__ W, int ldw, const bf16_t* __restrict__ X, size_t ldx, int mclamp, int kts,
;                  int nkt, int m0, f32x16 (&acc)[2][2], bf16_t* lds) {
;     ...
;   for (int kt = 0; kt < nkt; ++kt) {
;     const bool more = kt + 1 < nkt;
;     if (more) GM_GLOAD(kt + 1)
;     __builtin_amdgcn_sched_barrier(0);
;     {
;       const bf16_t* wb = lds + (kt & 1) * MID_E + (wn * 64 + lr) * LDT + lh * 8;
;       const bf16_t* xb = lds + (kt & 1) * MID_E + 128 * LDT + (wm * 64 + lr) * LDT + lh * 8;
; #pragma unroll
;       for (int ks = 0; ks < 4; ++ks) {
;         const bf16x8 a0 = *(const bf16x8*)(wb + ks * 16), a1 = *(const bf16x8*)(wb + 32 * LDT + ks * 16);
;         const bf16x8 b0 = *(const bf16x8*)(xb + ks * 16), b1 = *(const bf16x8*)(xb + 32 * LDT + ks * 16);
;         acc[0][0] = MFMA32(a0, b0, acc[0][0]); acc[0][1] = MFMA32(a0, b1, acc[0][1]);
;         acc[1][0] = MFMA32(a1, b0, acc[1][0]); acc[1][1] = MFMA32(a1, b1, acc[1][1]);
;       }
;     }
;     __builtin_amdgcn_sched_barrier(0);
;     if (more) GM_LSTORE((kt + 1) & 1)
;     __syncthreads();
;   }
	v_mfma_f32_32x32x16_bf16 v[0:15], v[120:123], v[128:131], v[0:15]
	ds_read_b128 v[160:163], v176 offset:0
	v_mfma_f32_32x32x16_bf16 v[16:31], v[120:123], v[132:135], v[16:31]
	ds_read_b128 v[152:155], v168 offset:32768
	s_add_u32 m0, s50, 0x4000
	s_nop 0
	global_load_lds_dwordx4 v180, s[46:47]
	v_mfma_f32_32x32x16_bf16 v[32:47], v[124:127], v[128:131], v[32:47]
	ds_read_b128 v[164:167], v176 offset:4096
	v_mfma_f32_32x32x16_bf16 v[48:63], v[124:127], v[132:135], v[48:63]
	ds_read_b128 v[156:159], v168 offset:36864
	global_load_lds_dwordx4 v181, s[46:47] offset:1024
	s_add_u32 s46, s46, 0x80
	s_addc_u32 s47, s47, 0
	v_mfma_f32_32x32x16_bf16 v[0:15], v[136:139], v[144:147], v[0:15]
	ds_read_b128 v[128:131], v177 offset:0
	v_mfma_f32_32x32x16_bf16 v[16:31], v[136:139], v[148:151], v[16:31]
	ds_read_b128 v[120:123], v169 offset:32768
	s_add_u32 m0, s51, 0x8000
	s_nop 0
	global_load_lds_dwordx4 v182, s[48:49]
	v_mfma_f32_32x32x16_bf16 v[32:47], v[140:143], v[144:147], v[32:47]
	ds_read_b128 v[132:135], v177 offset:4096
	v_mfma_f32_32x32x16_bf16 v[48:63], v[140:143], v[148:151], v[48:63]
	ds_read_b128 v[124:127], v169 offset:36864
	global_load_lds_dwordx4 v183, s[48:49] offset:1024
	s_waitcnt lgkmcnt(4)
	v_mfma_f32_32x32x16_bf16 v[0:15], v[152:155], v[160:163], v[0:15]
	ds_read_b128 v[144:147], v178 offset:0
	v_mfma_f32_32x32x16_bf16 v[16:31], v[152:155], v[164:167], v[16:31]
	ds_read_b128 v[136:139], v170 offset:32768
	global_load_lds_dwordx4 v184, s[48:49] offset:2048
	v_mfma_f32_32x32x16_bf16 v[32:47], v[156:159], v[160:163], v[32:47]
	ds_read_b128 v[148:151], v178 offset:4096
	v_mfma_f32_32x32x16_bf16 v[48:63], v[156:159], v[164:167], v[48:63]
	ds_read_b128 v[140:143], v170 offset:36864
	global_load_lds_dwordx4 v185, s[48:49] offset:3072
	s_add_u32 s48, s48, 0x80
	s_addc_u32 s49, s49, 0
	ds_read_b128 v[160:163], v179 offset:0
	ds_read_b128 v[152:155], v171 offset:32768
	ds_read_b128 v[164:167], v179 offset:4096
	ds_read_b128 v[156:159], v171 offset:36864
	s_waitcnt lgkmcnt(8)
	v_mfma_f32_32x32x16_bf16 v[0:15], v[120:123], v[128:131], v[0:15]
	v_mfma_f32_32x32x16_bf16 v[16:31], v[120:123], v[132:135], v[16:31]
	v_mfma_f32_32x32x16_bf16 v[32:47], v[124:127], v[128:131], v[32:47]
	v_mfma_f32_32x32x16_bf16 v[48:63], v[124:127], v[132:135], v[48:63]
	s_waitcnt vmcnt(6) lgkmcnt(0)
	s_barrier
	v_mfma_f32_32x32x16_bf16 v[0:15], v[136:139], v[144:147], v[0:15]
	ds_read_b128 v[128:131], v172 offset:0
	v_mfma_f32_32x32x16_bf16 v[16:31], v[136:139], v[148:151], v[16:31]
	ds_read_b128 v[120:123], v168 offset:0
	s_add_u32 m0, s50, 0x8000
	s_nop 0
	global_load_lds_dwordx4 v180, s[46:47]
	v_mfma_f32_32x32x16_bf16 v[32:47], v[140:143], v[144:147], v[32:47]
	ds_read_b128 v[132:135], v172 offset:4096
	v_mfma_f32_32x32x16_bf16 v[48:63], v[140:143], v[148:151], v[48:63]
	ds_read_b128 v[124:127], v168 offset:4096
	global_load_lds_dwordx4 v181, s[46:47] offset:1024
	s_add_u32 s46, s46, 0x80
	s_addc_u32 s47, s47, 0
	v_mfma_f32_32x32x16_bf16 v[0:15], v[152:155], v[160:163], v[0:15]
	ds_read_b128 v[144:147], v173 offset:0
	v_mfma_f32_32x32x16_bf16 v[16:31], v[152:155], v[164:167], v[16:31]
	ds_read_b128 v[136:139], v169 offset:0
	s_add_u32 m0, s51, 0x10000
	s_nop 0
	global_load_lds_dwordx4 v182, s[48:49]
	v_mfma_f32_32x32x16_bf16 v[32:47], v[156:159], v[160:163], v[32:47]
	ds_read_b128 v[148:151], v173 offset:4096
	v_mfma_f32_32x32x16_bf16 v[48:63], v[156:159], v[164:167], v[48:63]
	ds_read_b128 v[140:143], v169 offset:4096
	global_load_lds_dwordx4 v183, s[48:49] offset:1024
	s_waitcnt lgkmcnt(4)
	v_mfma_f32_32x32x16_bf16 v[0:15], v[120:123], v[128:131], v[0:15]
	ds_read_b128 v[160:163], v174 offset:0
	v_mfma_f32_32x32x16_bf16 v[16:31], v[120:123], v[132:135], v[16:31]
	ds_read_b128 v[152:155], v170 offset:0
	global_load_lds_dwordx4 v184, s[48:49] offset:2048
	v_mfma_f32_32x32x16_bf16 v[32:47], v[124:127], v[128:131], v[32:47]
	ds_read_b128 v[164:167], v174 offset:4096
	v_mfma_f32_32x32x16_bf16 v[48:63], v[124:127], v[132:135], v[48:63]
	ds_read_b128 v[156:159], v170 offset:4096
	global_load_lds_dwordx4 v185, s[48:49] offset:3072
	s_add_u32 s48, s48, 0x80
	s_addc_u32 s49, s49, 0
	ds_read_b128 v[128:131], v175 offset:0
	ds_read_b128 v[120:123], v171 offset:0
	ds_read_b128 v[132:135], v175 offset:4096
	ds_read_b128 v[124:127], v171 offset:4096
	s_waitcnt lgkmcnt(8)
	v_mfma_f32_32x32x16_bf16 v[0:15], v[136:139], v[144:147], v[0:15]
	v_mfma_f32_32x32x16_bf16 v[16:31], v[136:139], v[148:151], v[16:31]
	v_mfma_f32_32x32x16_bf16 v[32:47], v[140:143], v[144:147], v[32:47]
	v_mfma_f32_32x32x16_bf16 v[48:63], v[140:143], v[148:151], v[48:63]
	s_waitcnt vmcnt(6) lgkmcnt(0)
	s_barrier
; #define MFMA32(a, b, c) __builtin_amdgcn_mfma_f32_32x32x16_bf16((a), (b), (c), 0, 0, 0)
; DI void gemm_mid(const bf16_t* __restrict__ W, int ldw, const bf16_t* __restrict__ X, size_t ldx, int mclamp, int kts,
;                  int nkt, int m0, f32x16 (&acc)[2][2], bf16_t* lds) {
;     ...
;   for (int kt = 0; kt < nkt; ++kt) {
;     const bool more = kt + 1 < nkt;
;     if (more) GM_GLOAD(kt + 1)
;     __builtin_amdgcn_sched_barrier(0);
;     {
;       const bf16_t* wb = lds + (kt & 1) * MID_E + (wn * 64 + lr) * LDT + lh * 8;
;       const bf16_t* xb = lds + (kt & 1) * MID_E + 128 * LDT + (wm * 64 + lr) * LDT + lh * 8;
; #pragma unroll
;       for (int ks = 0; ks < 4; ++ks) {
;         const bf16x8 a0 = *(const bf16x8*)(wb + ks * 16), a1 = *(const bf16x8*)(wb + 32 * LDT + ks * 16);
;         const bf16x8 b0 = *(const bf16x8*)(xb + ks * 16), b1 = *(const bf16x8*)(xb + 32 * LDT + ks * 16);
;         acc[0][0] = MFMA32(a0, b0, acc[0][0]); acc[0][1] = MFMA32(a0, b1, acc[0][1]);
;         acc[1][0] = MFMA32(a1, b0, acc[1][0]); acc[1][1] = MFMA32(a1, b1, acc[1][1]);
;       }
;     }
;     __builtin_amdgcn_sched_barrier(0);
;     if (more) GM_LSTORE((kt + 1) & 1)
;     __syncthreads();
;   }
	v_mfma_f32_32x32x16_bf16 v[0:15], v[152:155], v[160:163], v[0:15]
	ds_read_b128 v[144:147], v172 offset:32768
	v_mfma_f32_32x32x16_bf16 v[16:31], v[152:155], v[164:167], v[16:31]
	ds_read_b128 v[136:139], v168 offset:16384
	s_mov_b32 m0, s50
	s_nop 0
	global_load_lds_dwordx4 v180, s[46:47]
	v_mfma_f32_32x32x16_bf16 v[32:47], v[156:159], v[160:163], v[32:47]
	ds_read_b128 v[148:151], v172 offset:36864
	v_mfma_f32_32x32x16_bf16 v[48:63], v[156:159], v[164:167], v[48:63]
	ds_read_b128 v[140:143], v168 offset:20480
	global_load_lds_dwordx4 v181, s[46:47] offset:1024
	s_add_u32 s46, s46, 0x80
	s_addc_u32 s47, s47, 0
	v_mfma_f32_32x32x16_bf16 v[0:15], v[120:123], v[128:131], v[0:15]
	ds_read_b128 v[160:163], v173 offset:32768
	v_mfma_f32_32x32x16_bf16 v[16:31], v[120:123], v[132:135], v[16:31]
	ds_read_b128 v[152:155], v169 offset:16384
	s_mov_b32 m0, s51
	s_nop 0
	global_load_lds_dwordx4 v182, s[48:49]
	v_mfma_f32_32x32x16_bf16 v[32:47], v[124:127], v[128:131], v[32:47]
	ds_read_b128 v[164:167], v173 offset:36864
	v_mfma_f32_32x32x16_bf16 v[48:63], v[124:127], v[132:135], v[48:63]
	ds_read_b128 v[156:159], v169 offset:20480
	global_load_lds_dwordx4 v183, s[48:49] offset:1024
	s_waitcnt lgkmcnt(4)
	v_mfma_f32_32x32x16_bf16 v[0:15], v[136:139], v[144:147], v[0:15]
	ds_read_b128 v[128:131], v174 offset:32768
	v_mfma_f32_32x32x16_bf16 v[16:31], v[136:139], v[148:151], v[16:31]
	ds_read_b128 v[120:123], v170 offset:16384
	global_load_lds_dwordx4 v184, s[48:49] offset:2048
	v_mfma_f32_32x32x16_bf16 v[32:47], v[140:143], v[144:147], v[32:47]
	ds_read_b128 v[132:135], v174 offset:36864
	v_mfma_f32_32x32x16_bf16 v[48:63], v[140:143], v[148:151], v[48:63]
	ds_read_b128 v[124:127], v170 offset:20480
	global_load_lds_dwordx4 v185, s[48:49] offset:3072
	s_add_u32 s48, s48, 0x80
	s_addc_u32 s49, s49, 0
	ds_read_b128 v[144:147], v175 offset:32768
	ds_read_b128 v[136:139], v171 offset:16384
	ds_read_b128 v[148:151], v175 offset:36864
	ds_read_b128 v[140:143], v171 offset:20480
	s_waitcnt lgkmcnt(8)
	v_mfma_f32_32x32x16_bf16 v[0:15], v[152:155], v[160:163], v[0:15]
	v_mfma_f32_32x32x16_bf16 v[16:31], v[152:155], v[164:167], v[16:31]
	v_mfma_f32_32x32x16_bf16 v[32:47], v[156:159], v[160:163], v[32:47]
	v_mfma_f32_32x32x16_bf16 v[48:63], v[156:159], v[164:167], v[48:63]
	s_waitcnt vmcnt(6) lgkmcnt(0)
	s_barrier
	v_mfma_f32_32x32x16_bf16 v[0:15], v[120:123], v[128:131], v[0:15]
	ds_read_b128 v[160:163], v176 offset:0
	v_mfma_f32_32x32x16_bf16 v[16:31], v[120:123], v[132:135], v[16:31]
	ds_read_b128 v[152:155], v168 offset:32768
	s_add_u32 m0, s50, 0x4000
	s_nop 0
	global_load_lds_dwordx4 v180, s[46:47]
	v_mfma_f32_32x32x16_bf16 v[32:47], v[124:127], v[128:131], v[32:47]
	ds_read_b128 v[164:167], v176 offset:4096
	v_mfma_f32_32x32x16_bf16 v[48:63], v[124:127], v[132:135], v[48:63]
	ds_read_b128 v[156:159], v168 offset:36864
	global_load_lds_dwordx4 v181, s[46:47] offset:1024
	s_add_u32 s46, s46, 0x80
	s_addc_u32 s47, s47, 0
	v_mfma_f32_32x32x16_bf16 v[0:15], v[136:139], v[144:147], v[0:15]
	ds_read_b128 v[128:131], v177 offset:0
	v_mfma_f32_32x32x16_bf16 v[16:31], v[136:139], v[148:151], v[16:31]
	ds_read_b128 v[120:123], v169 offset:32768
	s_add_u32 m0, s51, 0x8000
	s_nop 0
	global_load_lds_dwordx4 v182, s[48:49]
	v_mfma_f32_32x32x16_bf16 v[32:47], v[140:143], v[144:147], v[32:47]
	ds_read_b128 v[132:135], v177 offset:4096
	v_mfma_f32_32x32x16_bf16 v[48:63], v[140:143], v[148:151], v[48:63]
	ds_read_b128 v[124:127], v169 offset:36864
	global_load_lds_dwordx4 v183, s[48:49] offset:1024
	s_waitcnt lgkmcnt(4)
	v_mfma_f32_32x32x16_bf16 v[0:15], v[152:155], v[160:163], v[0:15]
	ds_read_b128 v[144:147], v178 offset:0
	v_mfma_f32_32x32x16_bf16 v[16:31], v[152:155], v[164:167], v[16:31]
	ds_read_b128 v[136:139], v170 offset:32768
	global_load_lds_dwordx4 v184, s[48:49] offset:2048
	v_mfma_f32_32x32x16_bf16 v[32:47], v[156:159], v[160:163], v[32:47]
	ds_read_b128 v[148:151], v178 offset:4096
	v_mfma_f32_32x32x16_bf16 v[48:63], v[156:159], v[164:167], v[48:63]
	ds_read_b128 v[140:143], v170 offset:36864
	global_load_lds_dwordx4 v185, s[48:49] offset:3072
	s_add_u32 s48, s48, 0x80
	s_addc_u32 s49, s49, 0
	ds_read_b128 v[160:163], v179 offset:0
	ds_read_b128 v[152:155], v171 offset:32768
	ds_read_b128 v[164:167], v179 offset:4096
	ds_read_b128 v[156:159], v171 offset:36864
	s_waitcnt lgkmcnt(8)
	v_mfma_f32_32x32x16_bf16 v[0:15], v[120:123], v[128:131], v[0:15]
	v_mfma_f32_32x32x16_bf16 v[16:31], v[120:123], v[132:135], v[16:31]
	v_mfma_f32_32x32x16_bf16 v[32:47], v[124:127], v[128:131], v[32:47]
	v_mfma_f32_32x32x16_bf16 v[48:63], v[124:127], v[132:135], v[48:63]
	s_waitcnt vmcnt(6) lgkmcnt(0)
	s_barrier
	v_mfma_f32_32x32x16_bf16 v[0:15], v[136:139], v[144:147], v[0:15]
	ds_read_b128 v[128:131], v172 offset:0
	v_mfma_f32_32x32x16_bf16 v[16:31], v[136:139], v[148:151], v[16:31]
	ds_read_b128 v[120:123], v168 offset:0
	v_mfma_f32_32x32x16_bf16 v[32:47], v[140:143], v[144:147], v[32:47]
	ds_read_b128 v[132:135], v172 offset:4096
	v_mfma_f32_32x32x16_bf16 v[48:63], v[140:143], v[148:151], v[48:63]
	ds_read_b128 v[124:127], v168 offset:4096
	v_mfma_f32_32x32x16_bf16 v[0:15], v[152:155], v[160:163], v[0:15]
	ds_read_b128 v[144:147], v173 offset:0
	v_mfma_f32_32x32x16_bf16 v[16:31], v[152:155], v[164:167], v[16:31]
	ds_read_b128 v[136:139], v169 offset:0
	v_mfma_f32_32x32x16_bf16 v[32:47], v[156:159], v[160:163], v[32:47]
	ds_read_b128 v[148:151], v173 offset:4096
	v_mfma_f32_32x32x16_bf16 v[48:63], v[156:159], v[164:167], v[48:63]
	ds_read_b128 v[140:143], v169 offset:4096
	s_waitcnt lgkmcnt(4)
	v_mfma_f32_32x32x16_bf16 v[0:15], v[120:123], v[128:131], v[0:15]
	ds_read_b128 v[160:163], v174 offset:0
	v_mfma_f32_32x32x16_bf16 v[16:31], v[120:123], v[132:135], v[16:31]
	ds_read_b128 v[152:155], v170 offset:0
	v_mfma_f32_32x32x16_bf16 v[32:47], v[124:127], v[128:131], v[32:47]
	ds_read_b128 v[164:167], v174 offset:4096
	v_mfma_f32_32x32x16_bf16 v[48:63], v[124:127], v[132:135], v[48:63]
	ds_read_b128 v[156:159], v170 offset:4096
	ds_read_b128 v[128:131], v175 offset:0
	ds_read_b128 v[120:123], v171 offset:0
	ds_read_b128 v[132:135], v175 offset:4096
	ds_read_b128 v[124:127], v171 offset:4096
	s_waitcnt lgkmcnt(8)
	v_mfma_f32_32x32x16_bf16 v[0:15], v[136:139], v[144:147], v[0:15]
	v_mfma_f32_32x32x16_bf16 v[16:31], v[136:139], v[148:151], v[16:31]
	v_mfma_f32_32x32x16_bf16 v[32:47], v[140:143], v[144:147], v[32:47]
	v_mfma_f32_32x32x16_bf16 v[48:63], v[140:143], v[148:151], v[48:63]
	s_waitcnt vmcnt(0) lgkmcnt(0)
	s_barrier
; DI void gemm_mid(const bf16_t* __restrict__ W, int ldw, const bf16_t* __restrict__ X, size_t ldx, int mclamp, int kts,
;                  int nkt, int m0, f32x16 (&acc)[2][2], bf16_t* lds) {
;     ...
;   for (int kt = 0; kt < nkt; ++kt) {
;     const bool more = kt + 1 < nkt;
;     if (more) GM_GLOAD(kt + 1)
;     __builtin_amdgcn_sched_barrier(0);
;     {
;       const bf16_t* wb = lds + (kt & 1) * MID_E + (wn * 64 + lr) * LDT + lh * 8;
;       const bf16_t* xb = lds + (kt & 1) * MID_E + 128 * LDT + (wm * 64 + lr) * LDT + lh * 8;
; #pragma unroll
;       for (int ks = 0; ks < 4; ++ks) {
;         const bf16x8 a0 = *(const bf16x8*)(wb + ks * 16), a1 = *(const bf16x8*)(wb + 32 * LDT + ks * 16);
;         const bf16x8 b0 = *(const bf16x8*)(xb + ks * 16), b1 = *(const bf16x8*)(xb + 32 * LDT + ks * 16);
;         acc[0][0] = MFMA32(a0, b0, acc[0][0]); acc[0][1] = MFMA32(a0, b1, acc[0][1]);
;         acc[1][0] = MFMA32(a1, b0, acc[1][0]); acc[1][1] = MFMA32(a1, b1, acc[1][1]);
;       }
;     }
;     __builtin_amdgcn_sched_barrier(0);
;     if (more) GM_LSTORE((kt + 1) & 1)
;     __syncthreads();
;   }
; DI void phase_merge(const P& p, int layer, bf16_t* sm, const Geo& ge) {
;     ...
;     for (int n3 = 0; n3 < 3; ++n3) {
;       const bf16_t* X = (const bf16_t*)(p.ws + (n3 == 0 ? O_AQ : (n3 == 1 ? O_BQ : O_CQ)));
;       f32x16 acc[2][2]; zero_acc(acc);
;       gemm_mid(W + ((size_t)n3 * 1024 + nt_ * 128) * 512, 512, X, 512, 1 << 30, 64, 8, mt_ * 256, acc, sm);
; #pragma unroll
;       for (int mt = 0; mt < 2; ++mt) {
;         const int m = mt_ * 256 + wm * 64 + mt * 32 + lr;
; #pragma unroll
;         for (int nt = 0; nt < 2; ++nt)
; #pragma unroll
;           for (int qd = 0; qd < 4; ++qd) {
;             const int n = nt_ * 128 + wn * 64 + nt * 32 + 8 * qd + 4 * lh;
;             typedef unsigned u32x2_t __attribute__((ext_vector_type(2)));
;             const u32x2_t gq_ = __builtin_nontemporal_load((const u32x2_t*)(mgs + ((size_t)((n3 * 1024 + n) >> 2) * T_ + m) * 4));
;             const uint2 gq = make_uint2(gq_[0], gq_[1]);
;             const unsigned z01 = zp[nt][mt][2 * qd], z23 = zp[nt][mt][2 * qd + 1];
;             const float v0 = bf2f((bf16_t)(z01 & 0xffff)) + bf2f((bf16_t)(gq.x & 0xffff)) * acc[nt][mt][4 * qd];
;             const float v1 = bf2f((bf16_t)(z01 >> 16)) + bf2f((bf16_t)(gq.x >> 16)) * acc[nt][mt][4 * qd + 1];
	v_mfma_f32_32x32x16_bf16 v[0:15], v[152:155], v[160:163], v[0:15]
	ds_read_b128 v[144:147], v172 offset:32768
	v_mfma_f32_32x32x16_bf16 v[16:31], v[152:155], v[164:167], v[16:31]
	ds_read_b128 v[136:139], v168 offset:16384
	v_mfma_f32_32x32x16_bf16 v[32:47], v[156:159], v[160:163], v[32:47]
	ds_read_b128 v[148:151], v172 offset:36864
	v_mfma_f32_32x32x16_bf16 v[48:63], v[156:159], v[164:167], v[48:63]
	ds_read_b128 v[140:143], v168 offset:20480
	v_mfma_f32_32x32x16_bf16 v[0:15], v[120:123], v[128:131], v[0:15]
	ds_read_b128 v[160:163], v173 offset:32768
	v_mfma_f32_32x32x16_bf16 v[16:31], v[120:123], v[132:135], v[16:31]
	ds_read_b128 v[152:155], v169 offset:16384
	v_mfma_f32_32x32x16_bf16 v[32:47], v[124:127], v[128:131], v[32:47]
	ds_read_b128 v[164:167], v173 offset:36864
	v_mfma_f32_32x32x16_bf16 v[48:63], v[124:127], v[132:135], v[48:63]
	ds_read_b128 v[156:159], v169 offset:20480
	s_waitcnt lgkmcnt(4)
	v_mfma_f32_32x32x16_bf16 v[0:15], v[136:139], v[144:147], v[0:15]
	ds_read_b128 v[128:131], v174 offset:32768
	v_mfma_f32_32x32x16_bf16 v[16:31], v[136:139], v[148:151], v[16:31]
	ds_read_b128 v[120:123], v170 offset:16384
	v_mfma_f32_32x32x16_bf16 v[32:47], v[140:143], v[144:147], v[32:47]
	ds_read_b128 v[132:135], v174 offset:36864
	v_mfma_f32_32x32x16_bf16 v[48:63], v[140:143], v[148:151], v[48:63]
	ds_read_b128 v[124:127], v170 offset:20480
	ds_read_b128 v[144:147], v175 offset:32768
	ds_read_b128 v[136:139], v171 offset:16384
	ds_read_b128 v[148:151], v175 offset:36864
	ds_read_b128 v[140:143], v171 offset:20480
	s_waitcnt lgkmcnt(8)
	v_mfma_f32_32x32x16_bf16 v[0:15], v[152:155], v[160:163], v[0:15]
	v_mfma_f32_32x32x16_bf16 v[16:31], v[152:155], v[164:167], v[16:31]
	v_mfma_f32_32x32x16_bf16 v[32:47], v[156:159], v[160:163], v[32:47]
	v_mfma_f32_32x32x16_bf16 v[48:63], v[156:159], v[164:167], v[48:63]
	s_waitcnt lgkmcnt(0)
	s_barrier
	v_mfma_f32_32x32x16_bf16 v[0:15], v[120:123], v[128:131], v[0:15]
	v_mfma_f32_32x32x16_bf16 v[16:31], v[120:123], v[132:135], v[16:31]
	v_mfma_f32_32x32x16_bf16 v[32:47], v[124:127], v[128:131], v[32:47]
	v_mfma_f32_32x32x16_bf16 v[48:63], v[124:127], v[132:135], v[48:63]
	v_mfma_f32_32x32x16_bf16 v[0:15], v[136:139], v[144:147], v[0:15]
	v_mfma_f32_32x32x16_bf16 v[16:31], v[136:139], v[148:151], v[16:31]
	v_mfma_f32_32x32x16_bf16 v[32:47], v[140:143], v[144:147], v[32:47]
	v_mfma_f32_32x32x16_bf16 v[48:63], v[140:143], v[148:151], v[48:63]
	s_add_u32 s46, s46, 0xffc00
	s_addc_u32 s47, s47, 0
	s_add_u32 s48, s48, 0xfffc00
	s_addc_u32 s49, s49, 0
	s_mov_b32 m0, s50
	s_nop 0
	global_load_lds_dwordx4 v180, s[46:47]
	global_load_lds_dwordx4 v181, s[46:47] offset:1024
	s_add_u32 s46, s46, 0x80
	s_addc_u32 s47, s47, 0
	s_mov_b32 m0, s51
	s_nop 0
	global_load_lds_dwordx4 v182, s[48:49]
	global_load_lds_dwordx4 v183, s[48:49] offset:1024
	global_load_lds_dwordx4 v184, s[48:49] offset:2048
	global_load_lds_dwordx4 v185, s[48:49] offset:3072
	s_add_u32 s48, s48, 0x80
	s_addc_u32 s49, s49, 0
	s_add_u32 m0, s50, 0x4000
	s_nop 0
	global_load_lds_dwordx4 v180, s[46:47]
	global_load_lds_dwordx4 v181, s[46:47] offset:1024
	s_add_u32 s46, s46, 0x80
	s_addc_u32 s47, s47, 0
	s_add_u32 m0, s51, 0x8000
	s_nop 0
	global_load_lds_dwordx4 v182, s[48:49]
	global_load_lds_dwordx4 v183, s[48:49] offset:1024
	global_load_lds_dwordx4 v184, s[48:49] offset:2048
	global_load_lds_dwordx4 v185, s[48:49] offset:3072
	s_add_u32 s48, s48, 0x80
	s_addc_u32 s49, s49, 0
	s_add_u32 m0, s50, 0x8000
	s_nop 0
	global_load_lds_dwordx4 v180, s[46:47]
	global_load_lds_dwordx4 v181, s[46:47] offset:1024
	s_add_u32 s46, s46, 0x80
	s_addc_u32 s47, s47, 0
	s_add_u32 m0, s51, 0x10000
	s_nop 0
	global_load_lds_dwordx4 v182, s[48:49]
	global_load_lds_dwordx4 v183, s[48:49] offset:1024
	global_load_lds_dwordx4 v184, s[48:49] offset:2048
	global_load_lds_dwordx4 v185, s[48:49] offset:3072
	s_add_u32 s48, s48, 0x80
	s_addc_u32 s49, s49, 0
	v_lshlrev_b32_e32 v98, 16, v196
	v_and_b32_e32 v99, 0xffff0000, v196
	v_lshlrev_b32_e32 v100, 16, v197
	v_and_b32_e32 v101, 0xffff0000, v197
	v_lshlrev_b32_e32 v102, 16, v64
	v_and_b32_e32 v103, 0xffff0000, v64
	v_lshlrev_b32_e32 v104, 16, v65
	v_and_b32_e32 v105, 0xffff0000, v65
	v_fma_f32 v98, v0, v98, v102
	v_fma_f32 v99, v1, v99, v103
	v_fma_f32 v100, v2, v100, v104
	v_fma_f32 v101, v3, v101, v105
	v_cvt_pk_bf16_f32 v64, v98, v99
	v_cvt_pk_bf16_f32 v65, v100, v101
	v_lshlrev_b32_e32 v98, 16, v198
	v_and_b32_e32 v99, 0xffff0000, v198
	v_lshlrev_b32_e32 v100, 16, v199
	v_and_b32_e32 v101, 0xffff0000, v199
	v_lshlrev_b32_e32 v102, 16, v66
	v_and_b32_e32 v103, 0xffff0000, v66
	v_lshlrev_b32_e32 v104, 16, v67
	v_and_b32_e32 v105, 0xffff0000, v67
	v_fma_f32 v98, v4, v98, v102
	v_fma_f32 v99, v5, v99, v103
	v_fma_f32 v100, v6, v100, v104
	v_fma_f32 v101, v7, v101, v105
	v_cvt_pk_bf16_f32 v66, v98, v99
	v_cvt_pk_bf16_f32 v67, v100, v101
	v_lshlrev_b32_e32 v98, 16, v200
	v_and_b32_e32 v99, 0xffff0000, v200
	v_lshlrev_b32_e32 v100, 16, v201
	v_and_b32_e32 v101, 0xffff0000, v201
	v_lshlrev_b32_e32 v102, 16, v68
	v_and_b32_e32 v103, 0xffff0000, v68
	v_lshlrev_b32_e32 v104, 16, v69
	v_and_b32_e32 v105, 0xffff0000, v69
	v_fma_f32 v98, v8, v98, v102
	v_fma_f32 v99, v9, v99, v103
	v_fma_f32 v100, v10, v100, v104
	v_fma_f32 v101, v11, v101, v105
	v_cvt_pk_bf16_f32 v68, v98, v99
	v_cvt_pk_bf16_f32 v69, v100, v101
	v_lshlrev_b32_e32 v98, 16, v202
	v_and_b32_e32 v99, 0xffff0000, v202
	v_lshlrev_b32_e32 v100, 16, v203
	v_and_b32_e32 v101, 0xffff0000, v203
	v_lshlrev_b32_e32 v102, 16, v70
	v_and_b32_e32 v103, 0xffff0000, v70
	v_lshlrev_b32_e32 v104, 16, v71
	v_and_b32_e32 v105, 0xffff0000, v71
	v_fma_f32 v98, v12, v98, v102
; DI float bf2f(bf16_t b) { return __uint_as_float(((unsigned)b) << 16); }
; DI unsigned pack2(float a, float b) { f32x2_t v = {a, b}; bf16x2_t r = __builtin_convertvector(v, bf16x2_t); return __builtin_bit_cast(unsigned, r); }
; DI void phase_merge(const P& p, int layer, bf16_t* sm, const Geo& ge) {
;     ...
; #pragma unroll
;       for (int mt = 0; mt < 2; ++mt) {
;         const int m = mt_ * 256 + wm * 64 + mt * 32 + lr;
; #pragma unroll
;         for (int nt = 0; nt < 2; ++nt)
; #pragma unroll
;           for (int qd = 0; qd < 4; ++qd) {
;             const int n = nt_ * 128 + wn * 64 + nt * 32 + 8 * qd + 4 * lh;
;             typedef unsigned u32x2_t __attribute__((ext_vector_type(2)));
;             const u32x2_t gq_ = __builtin_nontemporal_load((const u32x2_t*)(mgs + ((size_t)((n3 * 1024 + n) >> 2) * T_ + m) * 4));
;             const uint2 gq = make_uint2(gq_[0], gq_[1]);
;             const unsigned z01 = zp[nt][mt][2 * qd], z23 = zp[nt][mt][2 * qd + 1];
;             const float v0 = bf2f((bf16_t)(z01 & 0xffff)) + bf2f((bf16_t)(gq.x & 0xffff)) * acc[nt][mt][4 * qd];
;             const float v1 = bf2f((bf16_t)(z01 >> 16)) + bf2f((bf16_t)(gq.x >> 16)) * acc[nt][mt][4 * qd + 1];
;             const float v2 = bf2f((bf16_t)(z23 & 0xffff)) + bf2f((bf16_t)(gq.y & 0xffff)) * acc[nt][mt][4 * qd + 2];
;             const float v3 = bf2f((bf16_t)(z23 >> 16)) + bf2f((bf16_t)(gq.y >> 16)) * acc[nt][mt][4 * qd + 3];
;             zp[nt][mt][2 * qd] = pack2(v0, v1);
;             zp[nt][mt][2 * qd + 1] = pack2(v2, v3);
;           }
	v_fma_f32 v99, v13, v99, v103
	v_fma_f32 v100, v14, v100, v104
	v_fma_f32 v101, v15, v101, v105
	v_cvt_pk_bf16_f32 v70, v98, v99
	v_cvt_pk_bf16_f32 v71, v100, v101
	v_lshlrev_b32_e32 v98, 16, v204
	v_and_b32_e32 v99, 0xffff0000, v204
	v_lshlrev_b32_e32 v100, 16, v205
	v_and_b32_e32 v101, 0xffff0000, v205
	v_lshlrev_b32_e32 v102, 16, v72
	v_and_b32_e32 v103, 0xffff0000, v72
	v_lshlrev_b32_e32 v104, 16, v73
	v_and_b32_e32 v105, 0xffff0000, v73
	v_fma_f32 v98, v32, v98, v102
	v_fma_f32 v99, v33, v99, v103
	v_fma_f32 v100, v34, v100, v104
	v_fma_f32 v101, v35, v101, v105
	v_cvt_pk_bf16_f32 v72, v98, v99
	v_cvt_pk_bf16_f32 v73, v100, v101
	v_lshlrev_b32_e32 v98, 16, v206
	v_and_b32_e32 v99, 0xffff0000, v206
	v_lshlrev_b32_e32 v100, 16, v207
	v_and_b32_e32 v101, 0xffff0000, v207
	v_lshlrev_b32_e32 v102, 16, v74
	v_and_b32_e32 v103, 0xffff0000, v74
	v_lshlrev_b32_e32 v104, 16, v75
	v_and_b32_e32 v105, 0xffff0000, v75
	v_fma_f32 v98, v36, v98, v102
	v_fma_f32 v99, v37, v99, v103
	v_fma_f32 v100, v38, v100, v104
	v_fma_f32 v101, v39, v101, v105
	v_cvt_pk_bf16_f32 v74, v98, v99
	v_cvt_pk_bf16_f32 v75, v100, v101
	v_lshlrev_b32_e32 v98, 16, v208
	v_and_b32_e32 v99, 0xffff0000, v208
	v_lshlrev_b32_e32 v100, 16, v209
	v_and_b32_e32 v101, 0xffff0000, v209
	v_lshlrev_b32_e32 v102, 16, v76
	v_and_b32_e32 v103, 0xffff0000, v76
	v_lshlrev_b32_e32 v104, 16, v77
	v_and_b32_e32 v105, 0xffff0000, v77
	v_fma_f32 v98, v40, v98, v102
	v_fma_f32 v99, v41, v99, v103
	v_fma_f32 v100, v42, v100, v104
	v_fma_f32 v101, v43, v101, v105
	v_cvt_pk_bf16_f32 v76, v98, v99
	v_cvt_pk_bf16_f32 v77, v100, v101
	v_lshlrev_b32_e32 v98, 16, v210
	v_and_b32_e32 v99, 0xffff0000, v210
	v_lshlrev_b32_e32 v100, 16, v211
	v_and_b32_e32 v101, 0xffff0000, v211
	v_lshlrev_b32_e32 v102, 16, v78
	v_and_b32_e32 v103, 0xffff0000, v78
	v_lshlrev_b32_e32 v104, 16, v79
	v_and_b32_e32 v105, 0xffff0000, v79
	v_fma_f32 v98, v44, v98, v102
	v_fma_f32 v99, v45, v99, v103
	v_fma_f32 v100, v46, v100, v104
	v_fma_f32 v101, v47, v101, v105
	v_cvt_pk_bf16_f32 v78, v98, v99
	v_cvt_pk_bf16_f32 v79, v100, v101
	v_lshlrev_b32_e32 v98, 16, v212
	v_and_b32_e32 v99, 0xffff0000, v212
	v_lshlrev_b32_e32 v100, 16, v213
	v_and_b32_e32 v101, 0xffff0000, v213
	v_lshlrev_b32_e32 v102, 16, v80
	v_and_b32_e32 v103, 0xffff0000, v80
	v_lshlrev_b32_e32 v104, 16, v81
	v_and_b32_e32 v105, 0xffff0000, v81
	v_fma_f32 v98, v16, v98, v102
	v_fma_f32 v99, v17, v99, v103
	v_fma_f32 v100, v18, v100, v104
	v_fma_f32 v101, v19, v101, v105
	v_cvt_pk_bf16_f32 v80, v98, v99
	v_cvt_pk_bf16_f32 v81, v100, v101
	v_lshlrev_b32_e32 v98, 16, v214
	v_and_b32_e32 v99, 0xffff0000, v214
	v_lshlrev_b32_e32 v100, 16, v215
	v_and_b32_e32 v101, 0xffff0000, v215
	v_lshlrev_b32_e32 v102, 16, v82
	v_and_b32_e32 v103, 0xffff0000, v82
	v_lshlrev_b32_e32 v104, 16, v83
	v_and_b32_e32 v105, 0xffff0000, v83
	v_fma_f32 v98, v20, v98, v102
	v_fma_f32 v99, v21, v99, v103
	v_fma_f32 v100, v22, v100, v104
	v_fma_f32 v101, v23, v101, v105
	v_cvt_pk_bf16_f32 v82, v98, v99
	v_cvt_pk_bf16_f32 v83, v100, v101
	v_lshlrev_b32_e32 v98, 16, v216
	v_and_b32_e32 v99, 0xffff0000, v216
	v_lshlrev_b32_e32 v100, 16, v217
	v_and_b32_e32 v101, 0xffff0000, v217
	v_lshlrev_b32_e32 v102, 16, v84
	v_and_b32_e32 v103, 0xffff0000, v84
	v_lshlrev_b32_e32 v104, 16, v85
	v_and_b32_e32 v105, 0xffff0000, v85
	v_fma_f32 v98, v24, v98, v102
	v_fma_f32 v99, v25, v99, v103
	v_fma_f32 v100, v26, v100, v104
	v_fma_f32 v101, v27, v101, v105
	v_cvt_pk_bf16_f32 v84, v98, v99
	v_cvt_pk_bf16_f32 v85, v100, v101
	v_lshlrev_b32_e32 v98, 16, v218
	v_and_b32_e32 v99, 0xffff0000, v218
	v_lshlrev_b32_e32 v100, 16, v219
	v_and_b32_e32 v101, 0xffff0000, v219
	v_lshlrev_b32_e32 v102, 16, v86
	v_and_b32_e32 v103, 0xffff0000, v86
	v_lshlrev_b32_e32 v104, 16, v87
	v_and_b32_e32 v105, 0xffff0000, v87
	v_fma_f32 v98, v28, v98, v102
	v_fma_f32 v99, v29, v99, v103
	v_fma_f32 v100, v30, v100, v104
	v_fma_f32 v101, v31, v101, v105
	v_cvt_pk_bf16_f32 v86, v98, v99
	v_cvt_pk_bf16_f32 v87, v100, v101
	v_lshlrev_b32_e32 v98, 16, v236
	v_and_b32_e32 v99, 0xffff0000, v236
	v_lshlrev_b32_e32 v100, 16, v237
	v_and_b32_e32 v101, 0xffff0000, v237
	v_lshlrev_b32_e32 v102, 16, v90
	v_and_b32_e32 v103, 0xffff0000, v90
	v_lshlrev_b32_e32 v104, 16, v91
	v_and_b32_e32 v105, 0xffff0000, v91
	v_fma_f32 v98, v48, v98, v102
	v_fma_f32 v99, v49, v99, v103
	v_fma_f32 v100, v50, v100, v104
	v_fma_f32 v101, v51, v101, v105
	v_cvt_pk_bf16_f32 v90, v98, v99
	v_cvt_pk_bf16_f32 v91, v100, v101
	v_lshlrev_b32_e32 v98, 16, v238
	v_and_b32_e32 v99, 0xffff0000, v238
	v_lshlrev_b32_e32 v100, 16, v239
	v_and_b32_e32 v101, 0xffff0000, v239
	v_lshlrev_b32_e32 v102, 16, v92
	v_and_b32_e32 v103, 0xffff0000, v92
	v_lshlrev_b32_e32 v104, 16, v93
	v_and_b32_e32 v105, 0xffff0000, v93
	v_fma_f32 v98, v52, v98, v102
	v_fma_f32 v99, v53, v99, v103
	v_fma_f32 v100, v54, v100, v104
	v_fma_f32 v101, v55, v101, v105
	v_cvt_pk_bf16_f32 v92, v98, v99
	v_cvt_pk_bf16_f32 v93, v100, v101
	v_lshlrev_b32_e32 v98, 16, v240
	v_and_b32_e32 v99, 0xffff0000, v240
	v_lshlrev_b32_e32 v100, 16, v241
	v_and_b32_e32 v101, 0xffff0000, v241
	v_lshlrev_b32_e32 v102, 16, v94
	v_and_b32_e32 v103, 0xffff0000, v94
	v_lshlrev_b32_e32 v104, 16, v95
	v_and_b32_e32 v105, 0xffff0000, v95
	v_fma_f32 v98, v56, v98, v102
	v_fma_f32 v99, v57, v99, v103
	v_fma_f32 v100, v58, v100, v104
	v_fma_f32 v101, v59, v101, v105
	v_cvt_pk_bf16_f32 v94, v98, v99
	v_cvt_pk_bf16_f32 v95, v100, v101
	v_lshlrev_b32_e32 v98, 16, v242
	v_and_b32_e32 v99, 0xffff0000, v242
	v_lshlrev_b32_e32 v100, 16, v243
	v_and_b32_e32 v101, 0xffff0000, v243
	v_lshlrev_b32_e32 v102, 16, v96
	v_and_b32_e32 v103, 0xffff0000, v96
; DI void gemm_mid(const bf16_t* __restrict__ W, int ldw, const bf16_t* __restrict__ X, size_t ldx, int mclamp, int kts,
;                  int nkt, int m0, f32x16 (&acc)[2][2], bf16_t* lds) {
;     ...
;   for (int kt = 0; kt < nkt; ++kt) {
;     const bool more = kt + 1 < nkt;
;     if (more) GM_GLOAD(kt + 1)
;     __builtin_amdgcn_sched_barrier(0);
;     {
;       const bf16_t* wb = lds + (kt & 1) * MID_E + (wn * 64 + lr) * LDT + lh * 8;
;       const bf16_t* xb = lds + (kt & 1) * MID_E + 128 * LDT + (wm * 64 + lr) * LDT + lh * 8;
; #pragma unroll
;       for (int ks = 0; ks < 4; ++ks) {
;         const bf16x8 a0 = *(const bf16x8*)(wb + ks * 16), a1 = *(const bf16x8*)(wb + 32 * LDT + ks * 16);
;         const bf16x8 b0 = *(const bf16x8*)(xb + ks * 16), b1 = *(const bf16x8*)(xb + 32 * LDT + ks * 16);
;         acc[0][0] = MFMA32(a0, b0, acc[0][0]); acc[0][1] = MFMA32(a0, b1, acc[0][1]);
;         acc[1][0] = MFMA32(a1, b0, acc[1][0]); acc[1][1] = MFMA32(a1, b1, acc[1][1]);
;       }
;     }
;     __builtin_amdgcn_sched_barrier(0);
;     if (more) GM_LSTORE((kt + 1) & 1)
; DI void phase_merge(const P& p, int layer, bf16_t* sm, const Geo& ge) {
;     ...
; #pragma unroll
;       for (int mt = 0; mt < 2; ++mt) {
;         const int m = mt_ * 256 + wm * 64 + mt * 32 + lr;
; #pragma unroll
;         for (int nt = 0; nt < 2; ++nt)
; #pragma unroll
;           for (int qd = 0; qd < 4; ++qd) {
;             const int n = nt_ * 128 + wn * 64 + nt * 32 + 8 * qd + 4 * lh;
;             typedef unsigned u32x2_t __attribute__((ext_vector_type(2)));
;             const u32x2_t gq_ = __builtin_nontemporal_load((const u32x2_t*)(mgs + ((size_t)((n3 * 1024 + n) >> 2) * T_ + m) * 4));
;             const uint2 gq = make_uint2(gq_[0], gq_[1]);
;             const unsigned z01 = zp[nt][mt][2 * qd], z23 = zp[nt][mt][2 * qd + 1];
;             const float v0 = bf2f((bf16_t)(z01 & 0xffff)) + bf2f((bf16_t)(gq.x & 0xffff)) * acc[nt][mt][4 * qd];
;             const float v1 = bf2f((bf16_t)(z01 >> 16)) + bf2f((bf16_t)(gq.x >> 16)) * acc[nt][mt][4 * qd + 1];
;             const float v2 = bf2f((bf16_t)(z23 & 0xffff)) + bf2f((bf16_t)(gq.y & 0xffff)) * acc[nt][mt][4 * qd + 2];
;             const float v3 = bf2f((bf16_t)(z23 >> 16)) + bf2f((bf16_t)(gq.y >> 16)) * acc[nt][mt][4 * qd + 3];
;             zp[nt][mt][2 * qd] = pack2(v0, v1);
;             zp[nt][mt][2 * qd + 1] = pack2(v2, v3);
;           }
	v_lshlrev_b32_e32 v104, 16, v97
	v_and_b32_e32 v105, 0xffff0000, v97
	v_fma_f32 v98, v60, v98, v102
	v_fma_f32 v99, v61, v99, v103
	v_fma_f32 v100, v62, v100, v104
	v_fma_f32 v101, v63, v101, v105
	v_cvt_pk_bf16_f32 v96, v98, v99
	v_cvt_pk_bf16_f32 v97, v100, v101
	v_add_u32_e32 v190, 0x4000000, v186
	global_load_dwordx2 v[196:197], v190, s[28:29] nt
	global_load_dwordx2 v[212:213], v190, s[28:29] offset:256 nt
	v_add_u32_e32 v191, 0x4040000, v186
	global_load_dwordx2 v[198:199], v191, s[28:29] nt
	global_load_dwordx2 v[214:215], v191, s[28:29] offset:256 nt
	v_add_u32_e32 v190, 0x4080000, v186
	global_load_dwordx2 v[200:201], v190, s[28:29] nt
	global_load_dwordx2 v[216:217], v190, s[28:29] offset:256 nt
	v_add_u32_e32 v191, 0x40c0000, v186
	global_load_dwordx2 v[202:203], v191, s[28:29] nt
	global_load_dwordx2 v[218:219], v191, s[28:29] offset:256 nt
	v_add_u32_e32 v190, 0x4100000, v186
	global_load_dwordx2 v[204:205], v190, s[28:29] nt
	global_load_dwordx2 v[236:237], v190, s[28:29] offset:256 nt
	v_add_u32_e32 v191, 0x4140000, v186
	global_load_dwordx2 v[206:207], v191, s[28:29] nt
	global_load_dwordx2 v[238:239], v191, s[28:29] offset:256 nt
	v_add_u32_e32 v190, 0x4180000, v186
	global_load_dwordx2 v[208:209], v190, s[28:29] nt
	global_load_dwordx2 v[240:241], v190, s[28:29] offset:256 nt
	v_add_u32_e32 v191, 0x41c0000, v186
	global_load_dwordx2 v[210:211], v191, s[28:29] nt
	global_load_dwordx2 v[242:243], v191, s[28:29] offset:256 nt
	s_waitcnt vmcnt(28)
	s_barrier
	ds_read_b128 v[128:131], v172 offset:0
	ds_read_b128 v[120:123], v168 offset:0
	ds_read_b128 v[132:135], v172 offset:4096
	ds_read_b128 v[124:127], v168 offset:4096
	ds_read_b128 v[144:147], v173 offset:0
	ds_read_b128 v[136:139], v169 offset:0
	ds_read_b128 v[148:151], v173 offset:4096
	ds_read_b128 v[140:143], v169 offset:4096
	s_waitcnt lgkmcnt(4)
	v_mfma_f32_32x32x16_bf16 v[0:15], v[120:123], v[128:131], 0
	ds_read_b128 v[160:163], v174 offset:0
	v_mfma_f32_32x32x16_bf16 v[16:31], v[120:123], v[132:135], 0
	ds_read_b128 v[152:155], v170 offset:0
	v_mfma_f32_32x32x16_bf16 v[32:47], v[124:127], v[128:131], 0
	ds_read_b128 v[164:167], v174 offset:4096
	v_mfma_f32_32x32x16_bf16 v[48:63], v[124:127], v[132:135], 0
	ds_read_b128 v[156:159], v170 offset:4096
	ds_read_b128 v[128:131], v175 offset:0
	ds_read_b128 v[120:123], v171 offset:0
	ds_read_b128 v[132:135], v175 offset:4096
	ds_read_b128 v[124:127], v171 offset:4096
	s_waitcnt lgkmcnt(8)
	v_mfma_f32_32x32x16_bf16 v[0:15], v[136:139], v[144:147], v[0:15]
	v_mfma_f32_32x32x16_bf16 v[16:31], v[136:139], v[148:151], v[16:31]
	v_mfma_f32_32x32x16_bf16 v[32:47], v[140:143], v[144:147], v[32:47]
	v_mfma_f32_32x32x16_bf16 v[48:63], v[140:143], v[148:151], v[48:63]
	s_waitcnt vmcnt(22) lgkmcnt(0)
	s_barrier
	v_mfma_f32_32x32x16_bf16 v[0:15], v[152:155], v[160:163], v[0:15]
	ds_read_b128 v[144:147], v172 offset:32768
	v_mfma_f32_32x32x16_bf16 v[16:31], v[152:155], v[164:167], v[16:31]
	ds_read_b128 v[136:139], v168 offset:16384
	s_mov_b32 m0, s50
	s_nop 0
	global_load_lds_dwordx4 v180, s[46:47]
	v_mfma_f32_32x32x16_bf16 v[32:47], v[156:159], v[160:163], v[32:47]
	ds_read_b128 v[148:151], v172 offset:36864
	v_mfma_f32_32x32x16_bf16 v[48:63], v[156:159], v[164:167], v[48:63]
	ds_read_b128 v[140:143], v168 offset:20480
	global_load_lds_dwordx4 v181, s[46:47] offset:1024
	s_add_u32 s46, s46, 0x80
	s_addc_u32 s47, s47, 0
	v_mfma_f32_32x32x16_bf16 v[0:15], v[120:123], v[128:131], v[0:15]
	ds_read_b128 v[160:163], v173 offset:32768
	v_mfma_f32_32x32x16_bf16 v[16:31], v[120:123], v[132:135], v[16:31]
	ds_read_b128 v[152:155], v169 offset:16384
	s_mov_b32 m0, s51
	s_nop 0
	global_load_lds_dwordx4 v182, s[48:49]
	v_mfma_f32_32x32x16_bf16 v[32:47], v[124:127], v[128:131], v[32:47]
	ds_read_b128 v[164:167], v173 offset:36864
	v_mfma_f32_32x32x16_bf16 v[48:63], v[124:127], v[132:135], v[48:63]
	ds_read_b128 v[156:159], v169 offset:20480
	global_load_lds_dwordx4 v183, s[48:49] offset:1024
	s_waitcnt lgkmcnt(4)
	v_mfma_f32_32x32x16_bf16 v[0:15], v[136:139], v[144:147], v[0:15]
	ds_read_b128 v[128:131], v174 offset:32768
	v_mfma_f32_32x32x16_bf16 v[16:31], v[136:139], v[148:151], v[16:31]
	ds_read_b128 v[120:123], v170 offset:16384
	global_load_lds_dwordx4 v184, s[48:49] offset:2048
	v_mfma_f32_32x32x16_bf16 v[32:47], v[140:143], v[144:147], v[32:47]
	ds_read_b128 v[132:135], v174 offset:36864
	v_mfma_f32_32x32x16_bf16 v[48:63], v[140:143], v[148:151], v[48:63]
	ds_read_b128 v[124:127], v170 offset:20480
	global_load_lds_dwordx4 v185, s[48:49] offset:3072
	s_add_u32 s48, s48, 0x80
	s_addc_u32 s49, s49, 0
	ds_read_b128 v[144:147], v175 offset:32768
	ds_read_b128 v[136:139], v171 offset:16384
	ds_read_b128 v[148:151], v175 offset:36864
	ds_read_b128 v[140:143], v171 offset:20480
	s_waitcnt lgkmcnt(8)
	v_mfma_f32_32x32x16_bf16 v[0:15], v[152:155], v[160:163], v[0:15]
	v_mfma_f32_32x32x16_bf16 v[16:31], v[152:155], v[164:167], v[16:31]
	v_mfma_f32_32x32x16_bf16 v[32:47], v[156:159], v[160:163], v[32:47]
	v_mfma_f32_32x32x16_bf16 v[48:63], v[156:159], v[164:167], v[48:63]
	s_waitcnt vmcnt(22) lgkmcnt(0)
	s_barrier
; #define MFMA32(a, b, c) __builtin_amdgcn_mfma_f32_32x32x16_bf16((a), (b), (c), 0, 0, 0)
; DI void gemm_mid(const bf16_t* __restrict__ W, int ldw, const bf16_t* __restrict__ X, size_t ldx, int mclamp, int kts,
;                  int nkt, int m0, f32x16 (&acc)[2][2], bf16_t* lds) {
;     ...
;   for (int kt = 0; kt < nkt; ++kt) {
;     const bool more = kt + 1 < nkt;
;     if (more) GM_GLOAD(kt + 1)
;     __builtin_amdgcn_sched_barrier(0);
;     {
;       const bf16_t* wb = lds + (kt & 1) * MID_E + (wn * 64 + lr) * LDT + lh * 8;
;       const bf16_t* xb = lds + (kt & 1) * MID_E + 128 * LDT + (wm * 64 + lr) * LDT + lh * 8;
; #pragma unroll
;       for (int ks = 0; ks < 4; ++ks) {
;         const bf16x8 a0 = *(const bf16x8*)(wb + ks * 16), a1 = *(const bf16x8*)(wb + 32 * LDT + ks * 16);
;         const bf16x8 b0 = *(const bf16x8*)(xb + ks * 16), b1 = *(const bf16x8*)(xb + 32 * LDT + ks * 16);
;         acc[0][0] = MFMA32(a0, b0, acc[0][0]); acc[0][1] = MFMA32(a0, b1, acc[0][1]);
;         acc[1][0] = MFMA32(a1, b0, acc[1][0]); acc[1][1] = MFMA32(a1, b1, acc[1][1]);
;       }
;     }
;     __builtin_amdgcn_sched_barrier(0);
;     if (more) GM_LSTORE((kt + 1) & 1)
;     __syncthreads();
;   }
	v_mfma_f32_32x32x16_bf16 v[0:15], v[120:123], v[128:131], v[0:15]
	ds_read_b128 v[160:163], v176 offset:0
	v_mfma_f32_32x32x16_bf16 v[16:31], v[120:123], v[132:135], v[16:31]
	ds_read_b128 v[152:155], v168 offset:32768
	s_add_u32 m0, s50, 0x4000
	s_nop 0
	global_load_lds_dwordx4 v180, s[46:47]
	v_mfma_f32_32x32x16_bf16 v[32:47], v[124:127], v[128:131], v[32:47]
	ds_read_b128 v[164:167], v176 offset:4096
	v_mfma_f32_32x32x16_bf16 v[48:63], v[124:127], v[132:135], v[48:63]
	ds_read_b128 v[156:159], v168 offset:36864
	global_load_lds_dwordx4 v181, s[46:47] offset:1024
	s_add_u32 s46, s46, 0x80
	s_addc_u32 s47, s47, 0
	v_mfma_f32_32x32x16_bf16 v[0:15], v[136:139], v[144:147], v[0:15]
	ds_read_b128 v[128:131], v177 offset:0
	v_mfma_f32_32x32x16_bf16 v[16:31], v[136:139], v[148:151], v[16:31]
	ds_read_b128 v[120:123], v169 offset:32768
	s_add_u32 m0, s51, 0x8000
	s_nop 0
	global_load_lds_dwordx4 v182, s[48:49]
	v_mfma_f32_32x32x16_bf16 v[32:47], v[140:143], v[144:147], v[32:47]
	ds_read_b128 v[132:135], v177 offset:4096
	v_mfma_f32_32x32x16_bf16 v[48:63], v[140:143], v[148:151], v[48:63]
	ds_read_b128 v[124:127], v169 offset:36864
	global_load_lds_dwordx4 v183, s[48:49] offset:1024
	s_waitcnt lgkmcnt(4)
	v_mfma_f32_32x32x16_bf16 v[0:15], v[152:155], v[160:163], v[0:15]
	ds_read_b128 v[144:147], v178 offset:0
	v_mfma_f32_32x32x16_bf16 v[16:31], v[152:155], v[164:167], v[16:31]
	ds_read_b128 v[136:139], v170 offset:32768
	global_load_lds_dwordx4 v184, s[48:49] offset:2048
	v_mfma_f32_32x32x16_bf16 v[32:47], v[156:159], v[160:163], v[32:47]
	ds_read_b128 v[148:151], v178 offset:4096
	v_mfma_f32_32x32x16_bf16 v[48:63], v[156:159], v[164:167], v[48:63]
	ds_read_b128 v[140:143], v170 offset:36864
	global_load_lds_dwordx4 v185, s[48:49] offset:3072
	s_add_u32 s48, s48, 0x80
	s_addc_u32 s49, s49, 0
	ds_read_b128 v[160:163], v179 offset:0
	ds_read_b128 v[152:155], v171 offset:32768
	ds_read_b128 v[164:167], v179 offset:4096
	ds_read_b128 v[156:159], v171 offset:36864
	s_waitcnt lgkmcnt(8)
	v_mfma_f32_32x32x16_bf16 v[0:15], v[120:123], v[128:131], v[0:15]
	v_mfma_f32_32x32x16_bf16 v[16:31], v[120:123], v[132:135], v[16:31]
	v_mfma_f32_32x32x16_bf16 v[32:47], v[124:127], v[128:131], v[32:47]
	v_mfma_f32_32x32x16_bf16 v[48:63], v[124:127], v[132:135], v[48:63]
	s_waitcnt vmcnt(6) lgkmcnt(0)
	s_barrier
	v_mfma_f32_32x32x16_bf16 v[0:15], v[136:139], v[144:147], v[0:15]
	ds_read_b128 v[128:131], v172 offset:0
	v_mfma_f32_32x32x16_bf16 v[16:31], v[136:139], v[148:151], v[16:31]
	ds_read_b128 v[120:123], v168 offset:0
	s_add_u32 m0, s50, 0x8000
	s_nop 0
	global_load_lds_dwordx4 v180, s[46:47]
	v_mfma_f32_32x32x16_bf16 v[32:47], v[140:143], v[144:147], v[32:47]
	ds_read_b128 v[132:135], v172 offset:4096
	v_mfma_f32_32x32x16_bf16 v[48:63], v[140:143], v[148:151], v[48:63]
	ds_read_b128 v[124:127], v168 offset:4096
	global_load_lds_dwordx4 v181, s[46:47] offset:1024
	s_add_u32 s46, s46, 0x80
	s_addc_u32 s47, s47, 0
	v_mfma_f32_32x32x16_bf16 v[0:15], v[152:155], v[160:163], v[0:15]
	ds_read_b128 v[144:147], v173 offset:0
	v_mfma_f32_32x32x16_bf16 v[16:31], v[152:155], v[164:167], v[16:31]
	ds_read_b128 v[136:139], v169 offset:0
	s_add_u32 m0, s51, 0x10000
	s_nop 0
	global_load_lds_dwordx4 v182, s[48:49]
	v_mfma_f32_32x32x16_bf16 v[32:47], v[156:159], v[160:163], v[32:47]
	ds_read_b128 v[148:151], v173 offset:4096
	v_mfma_f32_32x32x16_bf16 v[48:63], v[156:159], v[164:167], v[48:63]
	ds_read_b128 v[140:143], v169 offset:4096
	global_load_lds_dwordx4 v183, s[48:49] offset:1024
	s_waitcnt lgkmcnt(4)
	v_mfma_f32_32x32x16_bf16 v[0:15], v[120:123], v[128:131], v[0:15]
	ds_read_b128 v[160:163], v174 offset:0
	v_mfma_f32_32x32x16_bf16 v[16:31], v[120:123], v[132:135], v[16:31]
	ds_read_b128 v[152:155], v170 offset:0
	global_load_lds_dwordx4 v184, s[48:49] offset:2048
	v_mfma_f32_32x32x16_bf16 v[32:47], v[124:127], v[128:131], v[32:47]
	ds_read_b128 v[164:167], v174 offset:4096
	v_mfma_f32_32x32x16_bf16 v[48:63], v[124:127], v[132:135], v[48:63]
	ds_read_b128 v[156:159], v170 offset:4096
	global_load_lds_dwordx4 v185, s[48:49] offset:3072
	s_add_u32 s48, s48, 0x80
	s_addc_u32 s49, s49, 0
	ds_read_b128 v[128:131], v175 offset:0
	ds_read_b128 v[120:123], v171 offset:0
	ds_read_b128 v[132:135], v175 offset:4096
	ds_read_b128 v[124:127], v171 offset:4096
	s_waitcnt lgkmcnt(8)
	v_mfma_f32_32x32x16_bf16 v[0:15], v[136:139], v[144:147], v[0:15]
	v_mfma_f32_32x32x16_bf16 v[16:31], v[136:139], v[148:151], v[16:31]
	v_mfma_f32_32x32x16_bf16 v[32:47], v[140:143], v[144:147], v[32:47]
	v_mfma_f32_32x32x16_bf16 v[48:63], v[140:143], v[148:151], v[48:63]
	s_waitcnt vmcnt(6) lgkmcnt(0)
	s_barrier
; #define MFMA32(a, b, c) __builtin_amdgcn_mfma_f32_32x32x16_bf16((a), (b), (c), 0, 0, 0)
; DI void gemm_mid(const bf16_t* __restrict__ W, int ldw, const bf16_t* __restrict__ X, size_t ldx, int mclamp, int kts,
;                  int nkt, int m0, f32x16 (&acc)[2][2], bf16_t* lds) {
;     ...
;   for (int kt = 0; kt < nkt; ++kt) {
;     const bool more = kt + 1 < nkt;
;     if (more) GM_GLOAD(kt + 1)
;     __builtin_amdgcn_sched_barrier(0);
;     {
;       const bf16_t* wb = lds + (kt & 1) * MID_E + (wn * 64 + lr) * LDT + lh * 8;
;       const bf16_t* xb = lds + (kt & 1) * MID_E + 128 * LDT + (wm * 64 + lr) * LDT + lh * 8;
; #pragma unroll
;       for (int ks = 0; ks < 4; ++ks) {
;         const bf16x8 a0 = *(const bf16x8*)(wb + ks * 16), a1 = *(const bf16x8*)(wb + 32 * LDT + ks * 16);
;         const bf16x8 b0 = *(const bf16x8*)(xb + ks * 16), b1 = *(const bf16x8*)(xb + 32 * LDT + ks * 16);
;         acc[0][0] = MFMA32(a0, b0, acc[0][0]); acc[0][1] = MFMA32(a0, b1, acc[0][1]);
;         acc[1][0] = MFMA32(a1, b0, acc[1][0]); acc[1][1] = MFMA32(a1, b1, acc[1][1]);
;       }
;     }
;     __builtin_amdgcn_sched_barrier(0);
;     if (more) GM_LSTORE((kt + 1) & 1)
;     __syncthreads();
;   }
	v_mfma_f32_32x32x16_bf16 v[0:15], v[152:155], v[160:163], v[0:15]
	ds_read_b128 v[144:147], v172 offset:32768
	v_mfma_f32_32x32x16_bf16 v[16:31], v[152:155], v[164:167], v[16:31]
	ds_read_b128 v[136:139], v168 offset:16384
	s_mov_b32 m0, s50
	s_nop 0
	global_load_lds_dwordx4 v180, s[46:47]
	v_mfma_f32_32x32x16_bf16 v[32:47], v[156:159], v[160:163], v[32:47]
	ds_read_b128 v[148:151], v172 offset:36864
	v_mfma_f32_32x32x16_bf16 v[48:63], v[156:159], v[164:167], v[48:63]
	ds_read_b128 v[140:143], v168 offset:20480
	global_load_lds_dwordx4 v181, s[46:47] offset:1024
	s_add_u32 s46, s46, 0x80
	s_addc_u32 s47, s47, 0
	v_mfma_f32_32x32x16_bf16 v[0:15], v[120:123], v[128:131], v[0:15]
	ds_read_b128 v[160:163], v173 offset:32768
	v_mfma_f32_32x32x16_bf16 v[16:31], v[120:123], v[132:135], v[16:31]
	ds_read_b128 v[152:155], v169 offset:16384
	s_mov_b32 m0, s51
	s_nop 0
	global_load_lds_dwordx4 v182, s[48:49]
	v_mfma_f32_32x32x16_bf16 v[32:47], v[124:127], v[128:131], v[32:47]
	ds_read_b128 v[164:167], v173 offset:36864
	v_mfma_f32_32x32x16_bf16 v[48:63], v[124:127], v[132:135], v[48:63]
	ds_read_b128 v[156:159], v169 offset:20480
	global_load_lds_dwordx4 v183, s[48:49] offset:1024
	s_waitcnt lgkmcnt(4)
	v_mfma_f32_32x32x16_bf16 v[0:15], v[136:139], v[144:147], v[0:15]
	ds_read_b128 v[128:131], v174 offset:32768
	v_mfma_f32_32x32x16_bf16 v[16:31], v[136:139], v[148:151], v[16:31]
	ds_read_b128 v[120:123], v170 offset:16384
	global_load_lds_dwordx4 v184, s[48:49] offset:2048
	v_mfma_f32_32x32x16_bf16 v[32:47], v[140:143], v[144:147], v[32:47]
	ds_read_b128 v[132:135], v174 offset:36864
	v_mfma_f32_32x32x16_bf16 v[48:63], v[140:143], v[148:151], v[48:63]
	ds_read_b128 v[124:127], v170 offset:20480
	global_load_lds_dwordx4 v185, s[48:49] offset:3072
	s_add_u32 s48, s48, 0x80
	s_addc_u32 s49, s49, 0
	ds_read_b128 v[144:147], v175 offset:32768
	ds_read_b128 v[136:139], v171 offset:16384
	ds_read_b128 v[148:151], v175 offset:36864
	ds_read_b128 v[140:143], v171 offset:20480
	s_waitcnt lgkmcnt(8)
	v_mfma_f32_32x32x16_bf16 v[0:15], v[152:155], v[160:163], v[0:15]
	v_mfma_f32_32x32x16_bf16 v[16:31], v[152:155], v[164:167], v[16:31]
	v_mfma_f32_32x32x16_bf16 v[32:47], v[156:159], v[160:163], v[32:47]
	v_mfma_f32_32x32x16_bf16 v[48:63], v[156:159], v[164:167], v[48:63]
	s_waitcnt vmcnt(6) lgkmcnt(0)
	s_barrier
	v_mfma_f32_32x32x16_bf16 v[0:15], v[120:123], v[128:131], v[0:15]
	ds_read_b128 v[160:163], v176 offset:0
	v_mfma_f32_32x32x16_bf16 v[16:31], v[120:123], v[132:135], v[16:31]
	ds_read_b128 v[152:155], v168 offset:32768
	s_add_u32 m0, s50, 0x4000
	s_nop 0
	global_load_lds_dwordx4 v180, s[46:47]
	v_mfma_f32_32x32x16_bf16 v[32:47], v[124:127], v[128:131], v[32:47]
	ds_read_b128 v[164:167], v176 offset:4096
	v_mfma_f32_32x32x16_bf16 v[48:63], v[124:127], v[132:135], v[48:63]
	ds_read_b128 v[156:159], v168 offset:36864
	global_load_lds_dwordx4 v181, s[46:47] offset:1024
	s_add_u32 s46, s46, 0x80
	s_addc_u32 s47, s47, 0
	v_mfma_f32_32x32x16_bf16 v[0:15], v[136:139], v[144:147], v[0:15]
	ds_read_b128 v[128:131], v177 offset:0
	v_mfma_f32_32x32x16_bf16 v[16:31], v[136:139], v[148:151], v[16:31]
	ds_read_b128 v[120:123], v169 offset:32768
	s_add_u32 m0, s51, 0x8000
	s_nop 0
	global_load_lds_dwordx4 v182, s[48:49]
	v_mfma_f32_32x32x16_bf16 v[32:47], v[140:143], v[144:147], v[32:47]
	ds_read_b128 v[132:135], v177 offset:4096
	v_mfma_f32_32x32x16_bf16 v[48:63], v[140:143], v[148:151], v[48:63]
	ds_read_b128 v[124:127], v169 offset:36864
	global_load_lds_dwordx4 v183, s[48:49] offset:1024
	s_waitcnt lgkmcnt(4)
	v_mfma_f32_32x32x16_bf16 v[0:15], v[152:155], v[160:163], v[0:15]
	ds_read_b128 v[144:147], v178 offset:0
	v_mfma_f32_32x32x16_bf16 v[16:31], v[152:155], v[164:167], v[16:31]
	ds_read_b128 v[136:139], v170 offset:32768
	global_load_lds_dwordx4 v184, s[48:49] offset:2048
	v_mfma_f32_32x32x16_bf16 v[32:47], v[156:159], v[160:163], v[32:47]
	ds_read_b128 v[148:151], v178 offset:4096
	v_mfma_f32_32x32x16_bf16 v[48:63], v[156:159], v[164:167], v[48:63]
	ds_read_b128 v[140:143], v170 offset:36864
	global_load_lds_dwordx4 v185, s[48:49] offset:3072
	s_add_u32 s48, s48, 0x80
	s_addc_u32 s49, s49, 0
	ds_read_b128 v[160:163], v179 offset:0
	ds_read_b128 v[152:155], v171 offset:32768
	ds_read_b128 v[164:167], v179 offset:4096
	ds_read_b128 v[156:159], v171 offset:36864
	s_waitcnt lgkmcnt(8)
	v_mfma_f32_32x32x16_bf16 v[0:15], v[120:123], v[128:131], v[0:15]
	v_mfma_f32_32x32x16_bf16 v[16:31], v[120:123], v[132:135], v[16:31]
	v_mfma_f32_32x32x16_bf16 v[32:47], v[124:127], v[128:131], v[32:47]
	v_mfma_f32_32x32x16_bf16 v[48:63], v[124:127], v[132:135], v[48:63]
	s_waitcnt vmcnt(6) lgkmcnt(0)
	s_barrier
	v_mfma_f32_32x32x16_bf16 v[0:15], v[136:139], v[144:147], v[0:15]
	ds_read_b128 v[128:131], v172 offset:0
	v_mfma_f32_32x32x16_bf16 v[16:31], v[136:139], v[148:151], v[16:31]
	ds_read_b128 v[120:123], v168 offset:0
	v_mfma_f32_32x32x16_bf16 v[32:47], v[140:143], v[144:147], v[32:47]
	ds_read_b128 v[132:135], v172 offset:4096
	v_mfma_f32_32x32x16_bf16 v[48:63], v[140:143], v[148:151], v[48:63]
	ds_read_b128 v[124:127], v168 offset:4096
	v_mfma_f32_32x32x16_bf16 v[0:15], v[152:155], v[160:163], v[0:15]
	ds_read_b128 v[144:147], v173 offset:0
	v_mfma_f32_32x32x16_bf16 v[16:31], v[152:155], v[164:167], v[16:31]
	ds_read_b128 v[136:139], v169 offset:0
	v_mfma_f32_32x32x16_bf16 v[32:47], v[156:159], v[160:163], v[32:47]
	ds_read_b128 v[148:151], v173 offset:4096
	v_mfma_f32_32x32x16_bf16 v[48:63], v[156:159], v[164:167], v[48:63]
	ds_read_b128 v[140:143], v169 offset:4096
	s_waitcnt lgkmcnt(4)
	v_mfma_f32_32x32x16_bf16 v[0:15], v[120:123], v[128:131], v[0:15]
	ds_read_b128 v[160:163], v174 offset:0
	v_mfma_f32_32x32x16_bf16 v[16:31], v[120:123], v[132:135], v[16:31]
	ds_read_b128 v[152:155], v170 offset:0
	v_mfma_f32_32x32x16_bf16 v[32:47], v[124:127], v[128:131], v[32:47]
	ds_read_b128 v[164:167], v174 offset:4096
	v_mfma_f32_32x32x16_bf16 v[48:63], v[124:127], v[132:135], v[48:63]
	ds_read_b128 v[156:159], v170 offset:4096
	ds_read_b128 v[128:131], v175 offset:0
	ds_read_b128 v[120:123], v171 offset:0
	ds_read_b128 v[132:135], v175 offset:4096
	ds_read_b128 v[124:127], v171 offset:4096
	s_waitcnt lgkmcnt(8)
	v_mfma_f32_32x32x16_bf16 v[0:15], v[136:139], v[144:147], v[0:15]
	v_mfma_f32_32x32x16_bf16 v[16:31], v[136:139], v[148:151], v[16:31]
	v_mfma_f32_32x32x16_bf16 v[32:47], v[140:143], v[144:147], v[32:47]
	v_mfma_f32_32x32x16_bf16 v[48:63], v[140:143], v[148:151], v[48:63]
	s_waitcnt vmcnt(0) lgkmcnt(0)
	s_barrier
; #define MFMA32(a, b, c) __builtin_amdgcn_mfma_f32_32x32x16_bf16((a), (b), (c), 0, 0, 0)
; DI float bf2f(bf16_t b) { return __uint_as_float(((unsigned)b) << 16); }
; DI unsigned pack2(float a, float b) { f32x2_t v = {a, b}; bf16x2_t r = __builtin_convertvector(v, bf16x2_t); return __builtin_bit_cast(unsigned, r); }
; DI void gemm_mid(const bf16_t* __restrict__ W, int ldw, const bf16_t* __restrict__ X, size_t ldx, int mclamp, int kts,
;                  int nkt, int m0, f32x16 (&acc)[2][2], bf16_t* lds) {
;     ...
;       for (int ks = 0; ks < 4; ++ks) {
;         const bf16x8 a0 = *(const bf16x8*)(wb + ks * 16), a1 = *(const bf16x8*)(wb + 32 * LDT + ks * 16);
;         const bf16x8 b0 = *(const bf16x8*)(xb + ks * 16), b1 = *(const bf16x8*)(xb + 32 * LDT + ks * 16);
;         acc[0][0] = MFMA32(a0, b0, acc[0][0]); acc[0][1] = MFMA32(a0, b1, acc[0][1]);
;         acc[1][0] = MFMA32(a1, b0, acc[1][0]); acc[1][1] = MFMA32(a1, b1, acc[1][1]);
;       }
; DI void phase_merge(const P& p, int layer, bf16_t* sm, const Geo& ge) {
;     ...
;       for (int mt = 0; mt < 2; ++mt) {
;         const int m = mt_ * 256 + wm * 64 + mt * 32 + lr;
; #pragma unroll
;         for (int nt = 0; nt < 2; ++nt)
; #pragma unroll
;           for (int qd = 0; qd < 4; ++qd) {
;             const int n = nt_ * 128 + wn * 64 + nt * 32 + 8 * qd + 4 * lh;
;             typedef unsigned u32x2_t __attribute__((ext_vector_type(2)));
;             const u32x2_t gq_ = __builtin_nontemporal_load((const u32x2_t*)(mgs + ((size_t)((n3 * 1024 + n) >> 2) * T_ + m) * 4));
;             const uint2 gq = make_uint2(gq_[0], gq_[1]);
;             const unsigned z01 = zp[nt][mt][2 * qd], z23 = zp[nt][mt][2 * qd + 1];
;             const float v0 = bf2f((bf16_t)(z01 & 0xffff)) + bf2f((bf16_t)(gq.x & 0xffff)) * acc[nt][mt][4 * qd];
;             const float v1 = bf2f((bf16_t)(z01 >> 16)) + bf2f((bf16_t)(gq.x >> 16)) * acc[nt][mt][4 * qd + 1];
;             const float v2 = bf2f((bf16_t)(z23 & 0xffff)) + bf2f((bf16_t)(gq.y & 0xffff)) * acc[nt][mt][4 * qd + 2];
;             const float v3 = bf2f((bf16_t)(z23 >> 16)) + bf2f((bf16_t)(gq.y >> 16)) * acc[nt][mt][4 * qd + 3];
;             zp[nt][mt][2 * qd] = pack2(v0, v1);
;             zp[nt][mt][2 * qd + 1] = pack2(v2, v3);
;           }
;       }
	v_mfma_f32_32x32x16_bf16 v[0:15], v[152:155], v[160:163], v[0:15]
	ds_read_b128 v[144:147], v172 offset:32768
	v_mfma_f32_32x32x16_bf16 v[16:31], v[152:155], v[164:167], v[16:31]
	ds_read_b128 v[136:139], v168 offset:16384
	v_mfma_f32_32x32x16_bf16 v[32:47], v[156:159], v[160:163], v[32:47]
	ds_read_b128 v[148:151], v172 offset:36864
	v_mfma_f32_32x32x16_bf16 v[48:63], v[156:159], v[164:167], v[48:63]
	ds_read_b128 v[140:143], v168 offset:20480
	v_mfma_f32_32x32x16_bf16 v[0:15], v[120:123], v[128:131], v[0:15]
	ds_read_b128 v[160:163], v173 offset:32768
	v_mfma_f32_32x32x16_bf16 v[16:31], v[120:123], v[132:135], v[16:31]
	ds_read_b128 v[152:155], v169 offset:16384
	v_mfma_f32_32x32x16_bf16 v[32:47], v[124:127], v[128:131], v[32:47]
	ds_read_b128 v[164:167], v173 offset:36864
	v_mfma_f32_32x32x16_bf16 v[48:63], v[124:127], v[132:135], v[48:63]
	ds_read_b128 v[156:159], v169 offset:20480
	s_waitcnt lgkmcnt(4)
	v_mfma_f32_32x32x16_bf16 v[0:15], v[136:139], v[144:147], v[0:15]
	ds_read_b128 v[128:131], v174 offset:32768
	v_mfma_f32_32x32x16_bf16 v[16:31], v[136:139], v[148:151], v[16:31]
	ds_read_b128 v[120:123], v170 offset:16384
	v_mfma_f32_32x32x16_bf16 v[32:47], v[140:143], v[144:147], v[32:47]
	ds_read_b128 v[132:135], v174 offset:36864
	v_mfma_f32_32x32x16_bf16 v[48:63], v[140:143], v[148:151], v[48:63]
	ds_read_b128 v[124:127], v170 offset:20480
	ds_read_b128 v[144:147], v175 offset:32768
	ds_read_b128 v[136:139], v171 offset:16384
	ds_read_b128 v[148:151], v175 offset:36864
	ds_read_b128 v[140:143], v171 offset:20480
	s_waitcnt lgkmcnt(8)
	v_mfma_f32_32x32x16_bf16 v[0:15], v[152:155], v[160:163], v[0:15]
	v_mfma_f32_32x32x16_bf16 v[16:31], v[152:155], v[164:167], v[16:31]
	v_mfma_f32_32x32x16_bf16 v[32:47], v[156:159], v[160:163], v[32:47]
	v_mfma_f32_32x32x16_bf16 v[48:63], v[156:159], v[164:167], v[48:63]
	s_waitcnt lgkmcnt(0)
	s_barrier
	v_mfma_f32_32x32x16_bf16 v[0:15], v[120:123], v[128:131], v[0:15]
	v_mfma_f32_32x32x16_bf16 v[16:31], v[120:123], v[132:135], v[16:31]
	v_mfma_f32_32x32x16_bf16 v[32:47], v[124:127], v[128:131], v[32:47]
	v_mfma_f32_32x32x16_bf16 v[48:63], v[124:127], v[132:135], v[48:63]
	v_mfma_f32_32x32x16_bf16 v[0:15], v[136:139], v[144:147], v[0:15]
	v_mfma_f32_32x32x16_bf16 v[16:31], v[136:139], v[148:151], v[16:31]
	v_mfma_f32_32x32x16_bf16 v[32:47], v[140:143], v[144:147], v[32:47]
	v_mfma_f32_32x32x16_bf16 v[48:63], v[140:143], v[148:151], v[48:63]
	s_nop 15
	v_lshlrev_b32_e32 v98, 16, v196
	v_and_b32_e32 v99, 0xffff0000, v196
	v_lshlrev_b32_e32 v100, 16, v197
	v_and_b32_e32 v101, 0xffff0000, v197
	v_lshlrev_b32_e32 v102, 16, v64
	v_and_b32_e32 v103, 0xffff0000, v64
	v_lshlrev_b32_e32 v104, 16, v65
	v_and_b32_e32 v105, 0xffff0000, v65
	v_fma_f32 v98, v0, v98, v102
	v_fma_f32 v99, v1, v99, v103
	v_fma_f32 v100, v2, v100, v104
	v_fma_f32 v101, v3, v101, v105
	v_cvt_pk_bf16_f32 v64, v98, v99
	v_cvt_pk_bf16_f32 v65, v100, v101
	v_lshlrev_b32_e32 v98, 16, v198
	v_and_b32_e32 v99, 0xffff0000, v198
	v_lshlrev_b32_e32 v100, 16, v199
	v_and_b32_e32 v101, 0xffff0000, v199
	v_lshlrev_b32_e32 v102, 16, v66
	v_and_b32_e32 v103, 0xffff0000, v66
	v_lshlrev_b32_e32 v104, 16, v67
	v_and_b32_e32 v105, 0xffff0000, v67
	v_fma_f32 v98, v4, v98, v102
	v_fma_f32 v99, v5, v99, v103
	v_fma_f32 v100, v6, v100, v104
	v_fma_f32 v101, v7, v101, v105
	v_cvt_pk_bf16_f32 v66, v98, v99
	v_cvt_pk_bf16_f32 v67, v100, v101
	v_lshlrev_b32_e32 v98, 16, v200
	v_and_b32_e32 v99, 0xffff0000, v200
	v_lshlrev_b32_e32 v100, 16, v201
	v_and_b32_e32 v101, 0xffff0000, v201
	v_lshlrev_b32_e32 v102, 16, v68
	v_and_b32_e32 v103, 0xffff0000, v68
	v_lshlrev_b32_e32 v104, 16, v69
	v_and_b32_e32 v105, 0xffff0000, v69
	v_fma_f32 v98, v8, v98, v102
	v_fma_f32 v99, v9, v99, v103
	v_fma_f32 v100, v10, v100, v104
	v_fma_f32 v101, v11, v101, v105
	v_cvt_pk_bf16_f32 v68, v98, v99
	v_cvt_pk_bf16_f32 v69, v100, v101
	v_lshlrev_b32_e32 v98, 16, v202
	v_and_b32_e32 v99, 0xffff0000, v202
	v_lshlrev_b32_e32 v100, 16, v203
	v_and_b32_e32 v101, 0xffff0000, v203
	v_lshlrev_b32_e32 v102, 16, v70
	v_and_b32_e32 v103, 0xffff0000, v70
	v_lshlrev_b32_e32 v104, 16, v71
	v_and_b32_e32 v105, 0xffff0000, v71
	v_fma_f32 v98, v12, v98, v102
	v_fma_f32 v99, v13, v99, v103
	v_fma_f32 v100, v14, v100, v104
	v_fma_f32 v101, v15, v101, v105
	v_cvt_pk_bf16_f32 v70, v98, v99
	v_cvt_pk_bf16_f32 v71, v100, v101
	v_lshlrev_b32_e32 v98, 16, v204
	v_and_b32_e32 v99, 0xffff0000, v204
	v_lshlrev_b32_e32 v100, 16, v205
	v_and_b32_e32 v101, 0xffff0000, v205
	v_lshlrev_b32_e32 v102, 16, v72
	v_and_b32_e32 v103, 0xffff0000, v72
	v_lshlrev_b32_e32 v104, 16, v73
	v_and_b32_e32 v105, 0xffff0000, v73
	v_fma_f32 v98, v32, v98, v102
	v_fma_f32 v99, v33, v99, v103
	v_fma_f32 v100, v34, v100, v104
	v_fma_f32 v101, v35, v101, v105
	v_cvt_pk_bf16_f32 v72, v98, v99
	v_cvt_pk_bf16_f32 v73, v100, v101
	v_lshlrev_b32_e32 v98, 16, v206
	v_and_b32_e32 v99, 0xffff0000, v206
	v_lshlrev_b32_e32 v100, 16, v207
	v_and_b32_e32 v101, 0xffff0000, v207
	v_lshlrev_b32_e32 v102, 16, v74
	v_and_b32_e32 v103, 0xffff0000, v74
	v_lshlrev_b32_e32 v104, 16, v75
	v_and_b32_e32 v105, 0xffff0000, v75
	v_fma_f32 v98, v36, v98, v102
	v_fma_f32 v99, v37, v99, v103
	v_fma_f32 v100, v38, v100, v104
	v_fma_f32 v101, v39, v101, v105
	v_cvt_pk_bf16_f32 v74, v98, v99
	v_cvt_pk_bf16_f32 v75, v100, v101
	v_lshlrev_b32_e32 v98, 16, v208
	v_and_b32_e32 v99, 0xffff0000, v208
	v_lshlrev_b32_e32 v100, 16, v209
	v_and_b32_e32 v101, 0xffff0000, v209
	v_lshlrev_b32_e32 v102, 16, v76
	v_and_b32_e32 v103, 0xffff0000, v76
	v_lshlrev_b32_e32 v104, 16, v77
	v_and_b32_e32 v105, 0xffff0000, v77
	v_fma_f32 v98, v40, v98, v102
	v_fma_f32 v99, v41, v99, v103
; DI void phase_merge(const P& p, int layer, bf16_t* sm, const Geo& ge) {
;     ...
;     bf16_t* stg = sm + wv * (64 * 72);
; #pragma unroll
;     for (int mt = 0; mt < 2; ++mt)
; #pragma unroll
;       for (int nt = 0; nt < 2; ++nt)
; #pragma unroll
;         for (int qd = 0; qd < 4; ++qd)
;           *(uint2*)(stg + (mt * 32 + lr) * 72 + nt * 32 + 8 * qd + 4 * lh) = make_uint2(zp[nt][mt][2 * qd], zp[nt][mt][2 * qd + 1]);
; #pragma unroll
;     for (int it = 0; it < 8; ++it) {
;       const int row = it * 8 + (lane >> 3), c16 = lane & 7;
;       const u32x4 v = *(const u32x4*)(stg + row * 72 + c16 * 8);
;       *(u32x4*)(z + (size_t)(mt_ * 256 + wm * 64 + row) * LDK1 + nt_ * 128 + wn * 64 + c16 * 8) = v;
;     }
	v_fma_f32 v100, v42, v100, v104
	v_fma_f32 v101, v43, v101, v105
	v_cvt_pk_bf16_f32 v76, v98, v99
	v_cvt_pk_bf16_f32 v77, v100, v101
	v_lshlrev_b32_e32 v98, 16, v210
	v_and_b32_e32 v99, 0xffff0000, v210
	v_lshlrev_b32_e32 v100, 16, v211
	v_and_b32_e32 v101, 0xffff0000, v211
	v_lshlrev_b32_e32 v102, 16, v78
	v_and_b32_e32 v103, 0xffff0000, v78
	v_lshlrev_b32_e32 v104, 16, v79
	v_and_b32_e32 v105, 0xffff0000, v79
	v_fma_f32 v98, v44, v98, v102
	v_fma_f32 v99, v45, v99, v103
	v_fma_f32 v100, v46, v100, v104
	v_fma_f32 v101, v47, v101, v105
	v_cvt_pk_bf16_f32 v78, v98, v99
	v_cvt_pk_bf16_f32 v79, v100, v101
	v_lshlrev_b32_e32 v98, 16, v212
	v_and_b32_e32 v99, 0xffff0000, v212
	v_lshlrev_b32_e32 v100, 16, v213
	v_and_b32_e32 v101, 0xffff0000, v213
	v_lshlrev_b32_e32 v102, 16, v80
	v_and_b32_e32 v103, 0xffff0000, v80
	v_lshlrev_b32_e32 v104, 16, v81
	v_and_b32_e32 v105, 0xffff0000, v81
	v_fma_f32 v98, v16, v98, v102
	v_fma_f32 v99, v17, v99, v103
	v_fma_f32 v100, v18, v100, v104
	v_fma_f32 v101, v19, v101, v105
	v_cvt_pk_bf16_f32 v80, v98, v99
	v_cvt_pk_bf16_f32 v81, v100, v101
	v_lshlrev_b32_e32 v98, 16, v214
	v_and_b32_e32 v99, 0xffff0000, v214
	v_lshlrev_b32_e32 v100, 16, v215
	v_and_b32_e32 v101, 0xffff0000, v215
	v_lshlrev_b32_e32 v102, 16, v82
	v_and_b32_e32 v103, 0xffff0000, v82
	v_lshlrev_b32_e32 v104, 16, v83
	v_and_b32_e32 v105, 0xffff0000, v83
	v_fma_f32 v98, v20, v98, v102
	v_fma_f32 v99, v21, v99, v103
	v_fma_f32 v100, v22, v100, v104
	v_fma_f32 v101, v23, v101, v105
	v_cvt_pk_bf16_f32 v82, v98, v99
	v_cvt_pk_bf16_f32 v83, v100, v101
	v_lshlrev_b32_e32 v98, 16, v216
	v_and_b32_e32 v99, 0xffff0000, v216
	v_lshlrev_b32_e32 v100, 16, v217
	v_and_b32_e32 v101, 0xffff0000, v217
	v_lshlrev_b32_e32 v102, 16, v84
	v_and_b32_e32 v103, 0xffff0000, v84
	v_lshlrev_b32_e32 v104, 16, v85
	v_and_b32_e32 v105, 0xffff0000, v85
	v_fma_f32 v98, v24, v98, v102
	v_fma_f32 v99, v25, v99, v103
	v_fma_f32 v100, v26, v100, v104
	v_fma_f32 v101, v27, v101, v105
	v_cvt_pk_bf16_f32 v84, v98, v99
	v_cvt_pk_bf16_f32 v85, v100, v101
	v_lshlrev_b32_e32 v98, 16, v218
	v_and_b32_e32 v99, 0xffff0000, v218
	v_lshlrev_b32_e32 v100, 16, v219
	v_and_b32_e32 v101, 0xffff0000, v219
	v_lshlrev_b32_e32 v102, 16, v86
	v_and_b32_e32 v103, 0xffff0000, v86
	v_lshlrev_b32_e32 v104, 16, v87
	v_and_b32_e32 v105, 0xffff0000, v87
	v_fma_f32 v98, v28, v98, v102
	v_fma_f32 v99, v29, v99, v103
	v_fma_f32 v100, v30, v100, v104
	v_fma_f32 v101, v31, v101, v105
	v_cvt_pk_bf16_f32 v86, v98, v99
	v_cvt_pk_bf16_f32 v87, v100, v101
	v_lshlrev_b32_e32 v98, 16, v236
	v_and_b32_e32 v99, 0xffff0000, v236
	v_lshlrev_b32_e32 v100, 16, v237
	v_and_b32_e32 v101, 0xffff0000, v237
	v_lshlrev_b32_e32 v102, 16, v90
	v_and_b32_e32 v103, 0xffff0000, v90
	v_lshlrev_b32_e32 v104, 16, v91
	v_and_b32_e32 v105, 0xffff0000, v91
	v_fma_f32 v98, v48, v98, v102
	v_fma_f32 v99, v49, v99, v103
	v_fma_f32 v100, v50, v100, v104
	v_fma_f32 v101, v51, v101, v105
	v_cvt_pk_bf16_f32 v90, v98, v99
	v_cvt_pk_bf16_f32 v91, v100, v101
	v_lshlrev_b32_e32 v98, 16, v238
	v_and_b32_e32 v99, 0xffff0000, v238
	v_lshlrev_b32_e32 v100, 16, v239
	v_and_b32_e32 v101, 0xffff0000, v239
	v_lshlrev_b32_e32 v102, 16, v92
	v_and_b32_e32 v103, 0xffff0000, v92
	v_lshlrev_b32_e32 v104, 16, v93
	v_and_b32_e32 v105, 0xffff0000, v93
	v_fma_f32 v98, v52, v98, v102
	v_fma_f32 v99, v53, v99, v103
	v_fma_f32 v100, v54, v100, v104
	v_fma_f32 v101, v55, v101, v105
	v_cvt_pk_bf16_f32 v92, v98, v99
	v_cvt_pk_bf16_f32 v93, v100, v101
	v_lshlrev_b32_e32 v98, 16, v240
	v_and_b32_e32 v99, 0xffff0000, v240
	v_lshlrev_b32_e32 v100, 16, v241
	v_and_b32_e32 v101, 0xffff0000, v241
	v_lshlrev_b32_e32 v102, 16, v94
	v_and_b32_e32 v103, 0xffff0000, v94
	v_lshlrev_b32_e32 v104, 16, v95
	v_and_b32_e32 v105, 0xffff0000, v95
	v_fma_f32 v98, v56, v98, v102
	v_fma_f32 v99, v57, v99, v103
	v_fma_f32 v100, v58, v100, v104
	v_fma_f32 v101, v59, v101, v105
	v_cvt_pk_bf16_f32 v94, v98, v99
	v_cvt_pk_bf16_f32 v95, v100, v101
	v_lshlrev_b32_e32 v98, 16, v242
	v_and_b32_e32 v99, 0xffff0000, v242
	v_lshlrev_b32_e32 v100, 16, v243
	v_and_b32_e32 v101, 0xffff0000, v243
	v_lshlrev_b32_e32 v102, 16, v96
	v_and_b32_e32 v103, 0xffff0000, v96
	v_lshlrev_b32_e32 v104, 16, v97
	v_and_b32_e32 v105, 0xffff0000, v97
	v_fma_f32 v98, v60, v98, v102
	v_fma_f32 v99, v61, v99, v103
	v_fma_f32 v100, v62, v100, v104
	v_fma_f32 v101, v63, v101, v105
	v_cvt_pk_bf16_f32 v96, v98, v99
	v_cvt_pk_bf16_f32 v97, v100, v101
	ds_write_b64 v188, v[64:65] offset:0
	ds_write_b64 v188, v[66:67] offset:16
	ds_write_b64 v188, v[68:69] offset:32
	ds_write_b64 v188, v[70:71] offset:48
	ds_write_b64 v188, v[72:73] offset:64
	ds_write_b64 v188, v[74:75] offset:80
	ds_write_b64 v188, v[76:77] offset:96
	ds_write_b64 v188, v[78:79] offset:112
	ds_write_b64 v188, v[80:81] offset:4608
	ds_write_b64 v188, v[82:83] offset:4624
	ds_write_b64 v188, v[84:85] offset:4640
	ds_write_b64 v188, v[86:87] offset:4656
	ds_write_b64 v188, v[90:91] offset:4672
	ds_write_b64 v188, v[92:93] offset:4688
	ds_write_b64 v188, v[94:95] offset:4704
	ds_write_b64 v188, v[96:97] offset:4720
	s_waitcnt lgkmcnt(0)
	ds_read_b128 v[120:123], v189 offset:0
	ds_read_b128 v[124:127], v189 offset:1152
	ds_read_b128 v[128:131], v189 offset:2304
	ds_read_b128 v[132:135], v189 offset:3456
	ds_read_b128 v[136:139], v189 offset:4608
	ds_read_b128 v[140:143], v189 offset:5760
	ds_read_b128 v[144:147], v189 offset:6912
	ds_read_b128 v[148:151], v189 offset:8064
	s_waitcnt lgkmcnt(7)
	global_store_dwordx4 v187, v[120:123], s[56:57]
	s_waitcnt lgkmcnt(6)
	v_add_u32_e32 v187, 0x4400, v187
	global_store_dwordx4 v187, v[124:127], s[56:57]
	s_waitcnt lgkmcnt(5)
	v_add_u32_e32 v187, 0x4400, v187
	global_store_dwordx4 v187, v[128:131], s[56:57]
	s_waitcnt lgkmcnt(4)
	v_add_u32_e32 v187, 0x4400, v187
	global_store_dwordx4 v187, v[132:135], s[56:57]
	s_waitcnt lgkmcnt(3)
	v_add_u32_e32 v187, 0x4400, v187
	global_store_dwordx4 v187, v[136:139], s[56:57]
	s_waitcnt lgkmcnt(2)
	v_add_u32_e32 v187, 0x4400, v187
	global_store_dwordx4 v187, v[140:143], s[56:57]
	s_waitcnt lgkmcnt(1)
	v_add_u32_e32 v187, 0x4400, v187
	global_store_dwordx4 v187, v[144:147], s[56:57]
	s_waitcnt lgkmcnt(0)
	v_add_u32_e32 v187, 0x4400, v187
	global_store_dwordx4 v187, v[148:151], s[56:57]
	s_add_i32 s7, s7, s31
	s_add_i32 s6, s6, s36
	s_cmp_lt_i32 s8, 64
	s_cbranch_scc1 .LBB0_1090
